# plus kv_unit / ret_unit staging: the 8 / 16 staging loads issued back to back (each was waited right after issue), data-dependent unpack and ds_writes behind counted waits
# baseline (speedup 1.0000x reference)
; #define LAS __attribute__((address_space(3)))
; __device__ __forceinline__ unsigned pk2(float lo, float hi) { return pg8::cvt_pk_bf16(lo, hi); }
; __device__ __forceinline__ float fexp2(float x) { return __builtin_amdgcn_exp2f(x); }
; __device__ __forceinline__ float ret_log2gamma(int h) { return log2f(1.f - exp2f(-5.f - (float)h)); }
; template <bool SC> __device__ __forceinline__ void stage_tr(LAS bfu* dst, const bfu* src, int pitch, int tid, float lg) {
; #pragma unroll
;     for (int i = 0; i < 4; ++i) { const int id = tid + NTHR * i, c = id & 127, ch = id >> 7; const v4u v = *(const v4u*)(src + (size_t)c * pitch + ch * 8);
;         const float sc = SC ? fexp2(lg * (float)(127 - c)) : 1.f;
; #pragma unroll
;         for (int j = 0; j < 4; ++j) { unsigned w = v[j];
;             if (SC) w = pk2(bflo(w) * sc, bfhi(w) * sc);
;             dst[(ch * 8 + 2 * j) * TS + c] = (bfu)(w & 0xffffu); dst[(ch * 8 + 2 * j + 1) * TS + c] = (bfu)(w >> 16); } }
; __device__ __forceinline__ void kv_unit(LAS unsigned char* lds, const bfu* PROJ, float* KVT, int u) {
;     ...
;     const int bh = u >> 6, i = u & 63, b = bh / 6, h = bh % 6; const size_t row0 = (size_t)b * SEQ + (size_t)i * 128; const float lg = ret_log2gamma(h);
;     LAS bfu* Vt = (LAS bfu*)lds; LAS bfu* Kt = (LAS bfu*)(lds + TILE_B);
;     stage_tr<false>(Vt, PROJ + row0 * INW + C_RV + h * 128, INW, tid, 0.f);
;     stage_tr<true>(Kt, PROJ + row0 * INW + C_RK + h * 128, INW, tid, lg);
.LBB0_272:
	s_mov_b32 s22, 21
	s_ashr_i32 s23, s22, 31
	s_lshl_b64 s[22:23], s[22:23], 3
	s_add_u32 s22, s0, s22
	s_addc_u32 s23, s1, s23
	s_load_dwordx2 s[34:35], s[22:23], 0x0
	s_mov_b32 s22, 21
	s_ashr_i32 s23, s22, 31
	s_lshl_b64 s[22:23], s[22:23], 3
	s_add_u32 s22, s0, s22
	s_addc_u32 s23, s1, s23
	s_ashr_i32 s44, s40, 6
	s_load_dwordx2 s[46:47], s[22:23], 0x0
	s_mul_hi_i32 s22, s44, 0x2aaaaaab
	s_lshr_b32 s23, s22, 31
	s_add_i32 s22, s22, s23
	s_mul_i32 s23, s22, 6
	s_sub_i32 s41, s44, s23
	v_cvt_f32_i32_e32 v0, s41
	s_ashr_i32 s23, s22, 31
	s_lshl_b32 s45, s40, 7
	s_lshl_b64 s[22:23], s[22:23], 13
	v_sub_f32_e32 v0, 0xc0a00000, v0
	v_cmp_gt_f32_e32 vcc, s64, v0
	s_and_b32 s45, s45, 0x1f80
	s_or_b32 s22, s22, s45
	v_cndmask_b32_e32 v2, 0, v241, vcc
	v_add_f32_e32 v0, v0, v2
	v_exp_f32_e32 v0, v0
	s_and_b64 s[48:49], vcc, exec
	s_cselect_b32 s45, 0xffffffc0, 0
	s_mulk_i32 s23, 0x3200
	v_ldexp_f32 v0, v0, s45
	v_sub_f32_e32 v0, 1.0, v0
	v_cmp_gt_f32_e32 vcc, s52, v0
	s_and_b64 s[48:49], vcc, exec
	s_cselect_b32 s45, 32, 0
	v_ldexp_f32 v0, v0, s45
	s_mul_hi_u32 s45, s22, 0x3200
	s_add_i32 s45, s45, s23
	s_mulk_i32 s22, 0x3200
	v_log_f32_e32 v0, v0
	s_waitcnt lgkmcnt(0)
	s_add_u32 s34, s34, s22
	s_addc_u32 s35, s35, s45
	s_lshl_b32 s22, s41, 7
	v_mov_b32_e32 v8, v232
	s_ashr_i32 s23, s22, 31
	v_cndmask_b32_e32 v2, 0, v242, vcc
	s_lshl_b64 s[22:23], s[22:23], 1
	v_and_b32_e32 v4, 0x7f, v8
	v_sub_f32_e32 v17, v0, v2
	s_add_u32 s22, s34, s22
	v_mul_u32_u24_e32 v0, 0x1900, v4
	s_addc_u32 s23, s35, s23
	v_lshlrev_b32_e32 v0, 1, v0
	v_lshl_add_u64 v[2:3], s[22:23], 0, v[0:1]
	s_mov_b64 s[22:23], 0x1ce00000
	v_ashrrev_i32_e32 v0, 4, v8
	v_lshl_add_u64 v[14:15], v[2:3], 0, s[22:23]
	v_and_b32_e32 v2, -8, v0
	v_ashrrev_i32_e32 v3, 31, v2
	v_lshl_add_u64 v[18:19], v[2:3], 1, v[14:15]
	v_mul_lo_u32 v0, v2, s65
	v_lshlrev_b32_e32 v9, 1, v4
	global_load_dwordx4 v[50:53], v[18:19], off offset:3072
	v_add3_u32 v20, 0, v0, v9
	v_add_u32_e32 v0, 0x200, v8
	v_ashrrev_i32_e32 v0, 4, v0
	s_movk_i32 s22, 0x7f
	v_readfirstlane_b32 s20, v8
	s_ashr_i32 s20, s20, 2
	s_ashr_i32 s41, s40, 31
	v_and_b32_e32 v2, -8, v0
	v_ashrrev_i32_e32 v3, 31, v2
	v_lshl_add_u64 v[6:7], v[2:3], 1, v[14:15]
	v_mul_lo_u32 v0, v2, s65
	global_load_dwordx4 v[54:57], v[6:7], off offset:3072
	v_add3_u32 v21, 0, v0, v9
	v_add_u32_e32 v0, 0x400, v8
	v_ashrrev_i32_e32 v0, 4, v0
	v_and_b32_e32 v2, -8, v0
	v_ashrrev_i32_e32 v3, 31, v2
	v_lshl_add_u64 v[4:5], v[2:3], 1, v[14:15]
	global_load_dwordx4 v[58:61], v[4:5], off offset:3072
	v_mul_lo_u32 v0, v2, s65
	v_add3_u32 v22, 0, v0, v9
	v_add_u32_e32 v0, 0x600, v8
	v_ashrrev_i32_e32 v0, 4, v0
	v_and_b32_e32 v10, -8, v0
	v_ashrrev_i32_e32 v11, 31, v10
	v_lshl_add_u64 v[2:3], v[10:11], 1, v[14:15]
	v_mul_lo_u32 v0, v10, s65
	global_load_dwordx4 v[62:65], v[2:3], off offset:3072
	v_add3_u32 v9, 0, v0, v9
	v_bitop3_b32 v0, v8, s22, v8 bitop3:0xc
	v_cvt_f32_ubyte0_e32 v0, v0
	v_mul_f32_e32 v0, v17, v0
	v_exp_f32_e32 v0, v0
	v_bfi_b32 v17, -16, s20, v8
	s_mov_b32 s20, 0x30600000
	global_load_dwordx4 v[66:69], v[18:19], off offset:1536
	v_mov_b32_e32 v70, v0
	v_mov_b32_e32 v71, v1
	global_load_dwordx4 v[92:95], v[6:7], off offset:1536
	global_load_dwordx4 v[120:123], v[4:5], off offset:1536
	global_load_dwordx4 v[146:149], v[2:3], off offset:1536
	s_waitcnt vmcnt(7)
	ds_write_b16 v20, v50
	ds_write_b16_d16_hi v20, v50 offset:272
	ds_write_b16 v20, v51 offset:544
	ds_write_b16_d16_hi v20, v51 offset:816
	ds_write_b16 v20, v52 offset:1088
	ds_write_b16_d16_hi v20, v52 offset:1360
	ds_write_b16 v20, v53 offset:1632
	ds_write_b16_d16_hi v20, v53 offset:1904
	s_waitcnt vmcnt(6)
	ds_write_b16 v21, v54
	ds_write_b16_d16_hi v21, v54 offset:272
	ds_write_b16 v21, v55 offset:544
	ds_write_b16_d16_hi v21, v55 offset:816
	ds_write_b16 v21, v56 offset:1088
	ds_write_b16_d16_hi v21, v56 offset:1360
	ds_write_b16 v21, v57 offset:1632
	ds_write_b16_d16_hi v21, v57 offset:1904
	s_waitcnt vmcnt(5)
	ds_write_b16 v22, v58
	ds_write_b16_d16_hi v22, v58 offset:272
	ds_write_b16 v22, v59 offset:544
	ds_write_b16_d16_hi v22, v59 offset:816
	ds_write_b16 v22, v60 offset:1088
	ds_write_b16_d16_hi v22, v60 offset:1360
	ds_write_b16 v22, v61 offset:1632
	ds_write_b16_d16_hi v22, v61 offset:1904
	s_waitcnt vmcnt(4)
	ds_write_b16 v9, v62
	ds_write_b16_d16_hi v9, v62 offset:272
	ds_write_b16 v9, v63 offset:544
	ds_write_b16_d16_hi v9, v63 offset:816
	ds_write_b16 v9, v64 offset:1088
	ds_write_b16_d16_hi v9, v64 offset:1360
	ds_write_b16 v9, v65 offset:1632
	ds_write_b16_d16_hi v9, v65 offset:1904
	s_waitcnt vmcnt(3)
	v_lshlrev_b32_e32 v46, 16, v66
	v_and_b32_e32 v47, 0xffff0000, v66
	v_pk_mul_f32 v[72:73], v[70:71], v[46:47] op_sel_hi:[0,1]
	v_cvt_pk_bf16_f32 v49, v72, v73
	ds_write_b16 v20, v49 offset:34816
	ds_write_b16_d16_hi v20, v49 offset:35088
	v_lshlrev_b32_e32 v74, 16, v67
	v_and_b32_e32 v75, 0xffff0000, v67
	v_pk_mul_f32 v[76:77], v[70:71], v[74:75] op_sel_hi:[0,1]
	v_cvt_pk_bf16_f32 v78, v76, v77
	ds_write_b16 v20, v78 offset:35360
	ds_write_b16_d16_hi v20, v78 offset:35632
	v_lshlrev_b32_e32 v80, 16, v68
	v_and_b32_e32 v81, 0xffff0000, v68
	v_pk_mul_f32 v[82:83], v[70:71], v[80:81] op_sel_hi:[0,1]
	v_cvt_pk_bf16_f32 v79, v82, v83
	ds_write_b16 v20, v79 offset:35904
	ds_write_b16_d16_hi v20, v79 offset:36176
	v_lshlrev_b32_e32 v84, 16, v69
	v_and_b32_e32 v85, 0xffff0000, v69
	v_pk_mul_f32 v[86:87], v[70:71], v[84:85] op_sel_hi:[0,1]
	v_cvt_pk_bf16_f32 v88, v86, v87
	ds_write_b16 v20, v88 offset:36448
	ds_write_b16_d16_hi v20, v88 offset:36720
	s_waitcnt vmcnt(2)
; __device__ __forceinline__ unsigned pk2(float lo, float hi) { return pg8::cvt_pk_bf16(lo, hi); }
; __device__ __forceinline__ float fexp2(float x) { return __builtin_amdgcn_exp2f(x); }
; #define ZERO8(a) do { _Pragma("unroll") for (int t_ = 0; t_ < 8; ++t_) a[t_] = (f32x4){0.f, 0.f, 0.f, 0.f}; } while (0)
; template <bool SC> __device__ __forceinline__ void stage_tr(LAS bfu* dst, const bfu* src, int pitch, int tid, float lg) {
;     ...
;     for (int i = 0; i < 4; ++i) { const int id = tid + NTHR * i, c = id & 127, ch = id >> 7; const v4u v = *(const v4u*)(src + (size_t)c * pitch + ch * 8);
;         const float sc = SC ? fexp2(lg * (float)(127 - c)) : 1.f;
; #pragma unroll
;         for (int j = 0; j < 4; ++j) { unsigned w = v[j];
;             if (SC) w = pk2(bflo(w) * sc, bfhi(w) * sc);
;             dst[(ch * 8 + 2 * j) * TS + c] = (bfu)(w & 0xffffu); dst[(ch * 8 + 2 * j + 1) * TS + c] = (bfu)(w >> 16); } }
; __device__ __forceinline__ void kv_unit(LAS unsigned char* lds, const bfu* PROJ, float* KVT, int u) {
;     ...
;     __syncthreads();
;     const int fr = lane & 15, fq = lane >> 4, m0 = wid * 16; f32x4 acc[8]; ZERO8(acc);
	v_lshlrev_b32_e32 v96, 16, v92
	v_and_b32_e32 v97, 0xffff0000, v92
	v_pk_mul_f32 v[98:99], v[70:71], v[96:97] op_sel_hi:[0,1]
	v_cvt_pk_bf16_f32 v100, v98, v99
	ds_write_b16 v21, v100 offset:34816
	ds_write_b16_d16_hi v21, v100 offset:35088
	v_lshlrev_b32_e32 v102, 16, v93
	v_and_b32_e32 v103, 0xffff0000, v93
	v_pk_mul_f32 v[104:105], v[70:71], v[102:103] op_sel_hi:[0,1]
	v_cvt_pk_bf16_f32 v101, v104, v105
	ds_write_b16 v21, v101 offset:35360
	ds_write_b16_d16_hi v21, v101 offset:35632
	v_lshlrev_b32_e32 v106, 16, v94
	v_and_b32_e32 v107, 0xffff0000, v94
	v_pk_mul_f32 v[108:109], v[70:71], v[106:107] op_sel_hi:[0,1]
	v_cvt_pk_bf16_f32 v110, v108, v109
	ds_write_b16 v21, v110 offset:35904
	ds_write_b16_d16_hi v21, v110 offset:36176
	v_lshlrev_b32_e32 v112, 16, v95
	v_and_b32_e32 v113, 0xffff0000, v95
	v_pk_mul_f32 v[114:115], v[70:71], v[112:113] op_sel_hi:[0,1]
	v_cvt_pk_bf16_f32 v118, v114, v115
	ds_write_b16 v21, v118 offset:36448
	ds_write_b16_d16_hi v21, v118 offset:36720
	s_waitcnt vmcnt(1)
	v_lshlrev_b32_e32 v124, 16, v120
	v_and_b32_e32 v125, 0xffff0000, v120
	v_pk_mul_f32 v[126:127], v[70:71], v[124:125] op_sel_hi:[0,1]
	v_cvt_pk_bf16_f32 v116, v126, v127
	ds_write_b16 v22, v116 offset:34816
	ds_write_b16_d16_hi v22, v116 offset:35088
	v_lshlrev_b32_e32 v128, 16, v121
	v_and_b32_e32 v129, 0xffff0000, v121
	v_pk_mul_f32 v[130:131], v[70:71], v[128:129] op_sel_hi:[0,1]
	v_cvt_pk_bf16_f32 v111, v130, v131
	ds_write_b16 v22, v111 offset:35360
	ds_write_b16_d16_hi v22, v111 offset:35632
	v_lshlrev_b32_e32 v132, 16, v122
	v_and_b32_e32 v133, 0xffff0000, v122
	v_pk_mul_f32 v[134:135], v[70:71], v[132:133] op_sel_hi:[0,1]
	v_cvt_pk_bf16_f32 v136, v134, v135
	ds_write_b16 v22, v136 offset:35904
	ds_write_b16_d16_hi v22, v136 offset:36176
	v_lshlrev_b32_e32 v138, 16, v123
	v_and_b32_e32 v139, 0xffff0000, v123
	v_pk_mul_f32 v[140:141], v[70:71], v[138:139] op_sel_hi:[0,1]
	v_cvt_pk_bf16_f32 v144, v140, v141
	ds_write_b16 v22, v144 offset:36448
	ds_write_b16_d16_hi v22, v144 offset:36720
	s_waitcnt vmcnt(0)
	v_lshlrev_b32_e32 v150, 16, v146
	v_and_b32_e32 v151, 0xffff0000, v146
	v_pk_mul_f32 v[152:153], v[70:71], v[150:151] op_sel_hi:[0,1]
	v_cvt_pk_bf16_f32 v142, v152, v153
	ds_write_b16 v9, v142 offset:34816
	ds_write_b16_d16_hi v9, v142 offset:35088
	v_lshlrev_b32_e32 v154, 16, v147
	v_and_b32_e32 v155, 0xffff0000, v147
	v_pk_mul_f32 v[156:157], v[70:71], v[154:155] op_sel_hi:[0,1]
	v_cvt_pk_bf16_f32 v137, v156, v157
	ds_write_b16 v9, v137 offset:35360
	ds_write_b16_d16_hi v9, v137 offset:35632
	v_lshlrev_b32_e32 v158, 16, v148
	v_and_b32_e32 v159, 0xffff0000, v148
	v_pk_mul_f32 v[160:161], v[70:71], v[158:159] op_sel_hi:[0,1]
	v_cvt_pk_bf16_f32 v162, v160, v161
	ds_write_b16 v9, v162 offset:35904
	ds_write_b16_d16_hi v9, v162 offset:36176
	v_lshlrev_b32_e32 v164, 16, v149
	v_and_b32_e32 v165, 0xffff0000, v149
	v_pk_mul_f32 v[166:167], v[70:71], v[164:165] op_sel_hi:[0,1]
	v_cvt_pk_bf16_f32 v163, v166, v167
	ds_write_b16 v9, v163 offset:36448
	ds_write_b16_d16_hi v9, v163 offset:36720
	v_and_b32_e32 v0, 48, v8
	v_and_b32_e32 v9, 15, v8
	v_add_u32_e32 v8, 0, v0
	v_mad_u64_u32 v[2:3], s[22:23], v17, s65, v[8:9]
	v_mad_u32_u24 v3, v9, s65, v8
	s_waitcnt lgkmcnt(0)
	s_barrier
; #define ZERO8(a) do { _Pragma("unroll") for (int t_ = 0; t_ < 8; ++t_) a[t_] = (f32x4){0.f, 0.f, 0.f, 0.f}; } while (0)
; __device__ __forceinline__ void st_sc1_x4(float* p, f32x4 v) { st_sc1_u2(p, __float_as_uint(v[0]), __float_as_uint(v[1])); st_sc1_u2(p + 2, __float_as_uint(v[2]), __float_as_uint(v[3])); }
; __device__ __forceinline__ void kv_unit(LAS unsigned char* lds, const bfu* PROJ, float* KVT, int u) {
;     ...
;     const int fr = lane & 15, fq = lane >> 4, m0 = wid * 16; f32x4 acc[8]; ZERO8(acc);
;     wave_mma(acc, Vt, Kt, m0, fr, fq);
;     float* o = KVT + (size_t)u * 16384 + (m0 + fr) * 128 + 4 * fq;
; #pragma unroll
;     for (int t = 0; t < 8; ++t) st_sc1_x4(o + 16 * t, acc[t]);
; __global__ void __launch_bounds__(NTHR, 2) fwd(Args args) {
;     ...
;                 if (u < 768) { kv_unit(lds, PROJ, KVT, u); publish(cw + 64 + (u >> 6)); }
	ds_read_b128 v[4:7], v2
	ds_read_b128 v[8:11], v3 offset:34816
	ds_read_b128 v[12:15], v3 offset:39168
	ds_read_b128 v[18:21], v3 offset:43520
	ds_read_b128 v[22:25], v3 offset:47872
	ds_read_b128 v[26:29], v3 offset:52224
	ds_read_b128 v[30:33], v3 offset:56576
	ds_read_b128 v[34:37], v3 offset:60928
	ds_read_b128 v[38:41], v3 offset:65280
	s_waitcnt lgkmcnt(7)
	v_mfma_f32_16x16x32_bf16 v[8:11], v[8:11], v[4:7], 0
	s_lshl_b64 s[22:23], s[40:41], 16
	s_add_u32 s22, s46, s22
	s_addc_u32 s23, s47, s23
	s_waitcnt lgkmcnt(6)
	v_mfma_f32_16x16x32_bf16 v[12:15], v[12:15], v[4:7], 0
	s_waitcnt lgkmcnt(5)
	v_mfma_f32_16x16x32_bf16 v[18:21], v[18:21], v[4:7], 0
	s_waitcnt lgkmcnt(4)
	v_mfma_f32_16x16x32_bf16 v[22:25], v[22:25], v[4:7], 0
	s_waitcnt lgkmcnt(3)
	v_mfma_f32_16x16x32_bf16 v[26:29], v[26:29], v[4:7], 0
	s_waitcnt lgkmcnt(2)
	v_mfma_f32_16x16x32_bf16 v[30:33], v[30:33], v[4:7], 0
	s_waitcnt lgkmcnt(1)
	v_mfma_f32_16x16x32_bf16 v[34:37], v[34:37], v[4:7], 0
	s_waitcnt lgkmcnt(0)
	v_mfma_f32_16x16x32_bf16 v[4:7], v[38:41], v[4:7], 0
	ds_read_b128 v[38:41], v2 offset:64
	ds_read_b128 v[42:45], v3 offset:34880
	s_waitcnt lgkmcnt(0)
	v_mfma_f32_16x16x32_bf16 v[8:11], v[42:45], v[38:41], v[8:11]
	ds_read_b128 v[42:45], v3 offset:39232
	s_waitcnt lgkmcnt(0)
	v_mfma_f32_16x16x32_bf16 v[12:15], v[42:45], v[38:41], v[12:15]
	ds_read_b128 v[42:45], v3 offset:43584
	s_waitcnt lgkmcnt(0)
	v_mfma_f32_16x16x32_bf16 v[18:21], v[42:45], v[38:41], v[18:21]
	ds_read_b128 v[42:45], v3 offset:47936
	s_waitcnt lgkmcnt(0)
	v_mfma_f32_16x16x32_bf16 v[22:25], v[42:45], v[38:41], v[22:25]
	ds_read_b128 v[42:45], v3 offset:52288
	s_waitcnt lgkmcnt(0)
	v_mfma_f32_16x16x32_bf16 v[26:29], v[42:45], v[38:41], v[26:29]
	ds_read_b128 v[42:45], v3 offset:56640
	s_waitcnt lgkmcnt(0)
	v_mfma_f32_16x16x32_bf16 v[30:33], v[42:45], v[38:41], v[30:33]
	ds_read_b128 v[42:45], v3 offset:60992
	s_waitcnt lgkmcnt(0)
	v_mfma_f32_16x16x32_bf16 v[34:37], v[42:45], v[38:41], v[34:37]
	ds_read_b128 v[42:45], v3 offset:65344
	s_waitcnt lgkmcnt(0)
	v_mfma_f32_16x16x32_bf16 v[4:7], v[42:45], v[38:41], v[4:7]
	ds_read_b128 v[38:41], v2 offset:128
	ds_read_b128 v[42:45], v3 offset:34944
	s_waitcnt lgkmcnt(0)
	v_mfma_f32_16x16x32_bf16 v[8:11], v[42:45], v[38:41], v[8:11]
	ds_read_b128 v[42:45], v3 offset:39296
	s_waitcnt lgkmcnt(0)
	v_mfma_f32_16x16x32_bf16 v[12:15], v[42:45], v[38:41], v[12:15]
	ds_read_b128 v[42:45], v3 offset:43648
	s_waitcnt lgkmcnt(0)
	v_mfma_f32_16x16x32_bf16 v[18:21], v[42:45], v[38:41], v[18:21]
	ds_read_b128 v[42:45], v3 offset:48000
	s_waitcnt lgkmcnt(0)
	v_mfma_f32_16x16x32_bf16 v[22:25], v[42:45], v[38:41], v[22:25]
	ds_read_b128 v[42:45], v3 offset:52352
	s_waitcnt lgkmcnt(0)
	v_mfma_f32_16x16x32_bf16 v[26:29], v[42:45], v[38:41], v[26:29]
	ds_read_b128 v[42:45], v3 offset:56704
	s_waitcnt lgkmcnt(0)
	v_mfma_f32_16x16x32_bf16 v[30:33], v[42:45], v[38:41], v[30:33]
	ds_read_b128 v[42:45], v3 offset:61056
	s_waitcnt lgkmcnt(0)
	v_mfma_f32_16x16x32_bf16 v[34:37], v[42:45], v[38:41], v[34:37]
	ds_read_b128 v[42:45], v3 offset:65408
	s_waitcnt lgkmcnt(0)
	v_mfma_f32_16x16x32_bf16 v[4:7], v[42:45], v[38:41], v[4:7]
	ds_read_b128 v[38:41], v2 offset:192
	ds_read_b128 v[42:45], v3 offset:35008
	s_waitcnt lgkmcnt(0)
	v_mfma_f32_16x16x32_bf16 v[8:11], v[42:45], v[38:41], v[8:11]
	ds_read_b128 v[42:45], v3 offset:39360
	s_waitcnt lgkmcnt(0)
	v_mfma_f32_16x16x32_bf16 v[12:15], v[42:45], v[38:41], v[12:15]
	ds_read_b128 v[42:45], v3 offset:43712
	s_waitcnt lgkmcnt(0)
	v_mfma_f32_16x16x32_bf16 v[18:21], v[42:45], v[38:41], v[18:21]
	ds_read_b128 v[42:45], v3 offset:48064
	s_waitcnt lgkmcnt(0)
	v_mfma_f32_16x16x32_bf16 v[22:25], v[42:45], v[38:41], v[22:25]
	ds_read_b128 v[42:45], v3 offset:52416
	s_waitcnt lgkmcnt(0)
	v_mfma_f32_16x16x32_bf16 v[26:29], v[42:45], v[38:41], v[26:29]
	ds_read_b128 v[42:45], v3 offset:56768
	s_waitcnt lgkmcnt(0)
	v_mfma_f32_16x16x32_bf16 v[30:33], v[42:45], v[38:41], v[30:33]
	ds_read_b128 v[42:45], v3 offset:61120
	s_waitcnt lgkmcnt(0)
	v_mfma_f32_16x16x32_bf16 v[34:37], v[42:45], v[38:41], v[34:37]
	ds_read_b128 v[42:45], v3 offset:65472
	s_waitcnt lgkmcnt(0)
	v_mfma_f32_16x16x32_bf16 v[2:5], v[42:45], v[38:41], v[4:7]
	s_nop 2
	v_lshlrev_b32_e32 v6, 7, v17
	v_ashrrev_i32_e32 v7, 31, v6
	v_lshl_add_u64 v[6:7], v[6:7], 2, s[22:23]
	v_lshl_add_u64 v[6:7], v[6:7], 0, v[0:1]
	s_mov_b64 s[22:23], 0x30600000
	v_lshl_add_u64 v[38:39], v[6:7], 0, s[22:23]
	v_add_co_u32_e32 v6, vcc, s20, v6
	s_nop 1
	v_addc_co_u32_e32 v7, vcc, 0, v7, vcc
	global_store_dwordx4 v[38:39], v[8:11], off sc1
	global_store_dwordx4 v[38:39], v[12:15], off offset:64 sc1
	global_store_dwordx4 v[38:39], v[18:21], off offset:128 sc1
	global_store_dwordx4 v[38:39], v[22:25], off offset:192 sc1
	global_store_dwordx4 v[38:39], v[26:29], off offset:256 sc1
	global_store_dwordx4 v[38:39], v[30:33], off offset:320 sc1
	global_store_dwordx4 v[38:39], v[34:37], off offset:384 sc1
	global_store_dwordx4 v[38:39], v[2:5], off offset:448 sc1
	s_waitcnt vmcnt(0)
	s_barrier
	s_and_saveexec_b64 s[40:41], s[74:75]
	s_ashr_i32 s45, s44, 31
	s_lshl_b64 s[22:23], s[44:45], 2
	s_add_u32 s20, s4, s22
	s_addc_u32 s22, s5, s23
	s_add_u32 s34, s20, 0x200
	s_addc_u32 s35, s22, 0
	s_or_b64 s[42:43], s[42:43], exec
	s_or_b64 exec, exec, s[40:41]

; #define LAS __attribute__((address_space(3)))
; __device__ __forceinline__ unsigned pk2(float lo, float hi) { return pg8::cvt_pk_bf16(lo, hi); }
; __device__ __forceinline__ float fexp2(float x) { return __builtin_amdgcn_exp2f(x); }
; __device__ __forceinline__ float ret_log2gamma(int h) { return log2f(1.f - exp2f(-5.f - (float)h)); }
; __device__ __forceinline__ void stage_nat(LAS bfu* dst, const bfu* src, int pitch, int tid) {
; #pragma unroll
;     for (int i = 0; i < 4; ++i) { const int id = tid + NTHR * i, r = id >> 4, ch = id & 15; const v4u v = *(const v4u*)(src + (size_t)r * pitch + ch * 8); *(LAS v4u*)(dst + r * TS + ch * 8) = v; }
; }
; template <bool SC> __device__ __forceinline__ void stage_tr(LAS bfu* dst, const bfu* src, int pitch, int tid, float lg) {
; #pragma unroll
;     for (int i = 0; i < 4; ++i) { const int id = tid + NTHR * i, c = id & 127, ch = id >> 7; const v4u v = *(const v4u*)(src + (size_t)c * pitch + ch * 8);
;         const float sc = SC ? fexp2(lg * (float)(127 - c)) : 1.f;
; #pragma unroll
;         for (int j = 0; j < 4; ++j) { unsigned w = v[j];
;             if (SC) w = pk2(bflo(w) * sc, bfhi(w) * sc);
;             dst[(ch * 8 + 2 * j) * TS + c] = (bfu)(w & 0xffffu); dst[(ch * 8 + 2 * j + 1) * TS + c] = (bfu)(w >> 16); } }
; __device__ __forceinline__ void ret_unit(LAS unsigned char* lds, const bfu* PROJ, const bfu* RT, const float* gn_g, bfu* CAT, int u) {
;     ...
;     const int bh = u >> 6, i = u & 63, b = bh / 6, h = bh % 6; const size_t row0 = (size_t)b * SEQ + (size_t)i * 128; const float lg = ret_log2gamma(h);
;     LAS bfu* Qs = (LAS bfu*)lds; LAS bfu* Ks = (LAS bfu*)(lds + TILE_B); LAS bfu* Vt = (LAS bfu*)(lds + 2 * TILE_B); LAS bfu* Rt = (LAS bfu*)(lds + 3 * TILE_B);
;     const bfu* P0 = PROJ + row0 * INW + h * 128;
;     stage_nat(Qs, P0 + C_RQ, INW, tid); stage_nat(Ks, P0 + C_RK, INW, tid); stage_tr<false>(Vt, P0 + C_RV, INW, tid, 0.f); stage_nat(Rt, RT + (size_t)u * 16384, 128, tid);
.LBB0_410:
	s_or_b64 exec, exec, s[40:41]
	s_mov_b32 s22, 21
	s_barrier
	s_ashr_i32 s23, s22, 31
	s_lshl_b64 s[22:23], s[22:23], 3
	s_add_u32 s22, s0, s22
	s_addc_u32 s23, s1, s23
	s_load_dwordx2 s[48:49], s[22:23], 0x0
	s_mov_b32 s22, 21
	s_ashr_i32 s23, s22, 31
	s_lshl_b64 s[22:23], s[22:23], 3
	s_add_u32 s22, s0, s22
	s_addc_u32 s23, s1, s23
	s_load_dwordx2 s[40:41], s[22:23], 0x0
	s_mov_b32 s22, 3
	s_ashr_i32 s23, s22, 31
	s_lshl_b64 s[22:23], s[22:23], 3
	s_add_u32 s22, s0, s22
	s_addc_u32 s23, s1, s23
	s_load_dwordx2 s[22:23], s[22:23], 0x0
	v_mov_b32_e32 v10, v232
	v_readlane_b32 s91, v255, 54
	s_waitcnt lgkmcnt(0)
	s_add_u32 s20, s22, s36
	s_mov_b32 s22, 21
	s_addc_u32 s35, s23, s37
	s_ashr_i32 s23, s22, 31
	s_lshl_b64 s[22:23], s[22:23], 3
	s_add_u32 s22, s0, s22
	s_addc_u32 s23, s1, s23
	s_load_dwordx2 s[44:45], s[22:23], 0x0
	s_mul_hi_i32 s23, s34, 0x2aaaaaab
	s_lshr_b32 s46, s23, 31
	s_add_i32 s46, s23, s46
	s_mul_i32 s23, s46, 6
	s_sub_i32 s23, s34, s23
	v_cvt_f32_i32_e32 v0, s23
	s_ashr_i32 s47, s46, 31
	s_lshl_b32 s34, s92, 7
	s_lshl_b64 s[46:47], s[46:47], 13
	v_sub_f32_e32 v0, 0xc0a00000, v0
	v_cmp_gt_f32_e32 vcc, s64, v0
	s_and_b32 s34, s34, 0x1f80
	s_or_b32 s46, s46, s34
	v_cndmask_b32_e32 v2, 0, v241, vcc
	v_add_f32_e32 v0, v0, v2
	v_exp_f32_e32 v0, v0
	s_and_b64 s[50:51], vcc, exec
	s_cselect_b32 s34, 0xffffffc0, 0
	s_mul_hi_u32 s50, s46, 0x3200
	v_ldexp_f32 v0, v0, s34
	s_mul_i32 s34, s47, 0x3200
	s_add_i32 s50, s50, s34
	s_mul_i32 s34, s46, 0x3200
	s_add_u32 s34, s48, s34
	s_addc_u32 s48, s49, s50
	s_lshl_b32 s50, s23, 7
	s_ashr_i32 s51, s50, 31
	s_lshl_b64 s[52:53], s[50:51], 1
	s_add_u32 s23, s34, s52
	s_addc_u32 s34, s48, s53
	v_sub_f32_e32 v11, 1.0, v0
	s_add_u32 s56, s23, 0x1ce00000
	v_lshlrev_b32_e32 v0, 4, v10
	s_addc_u32 s57, s34, 0
	v_and_b32_e32 v0, 0xf0, v0
	v_lshl_add_u64 v[16:17], s[56:57], 0, v[0:1]
	v_ashrrev_i32_e32 v2, 4, v10
	v_mad_i64_i32 v[18:19], s[48:49], v2, s61, v[16:17]
	global_load_dwordx4 v[120:123], v[18:19], off
	v_add_u32_e32 v26, 0, v0
	v_mul_lo_u32 v27, v2, s65
	v_add_u32_e32 v28, v26, v27
	s_ashr_i32 s93, s92, 31
	v_ashrrev_i32_e32 v3, 31, v2
	v_readfirstlane_b32 s22, v10
	v_bfe_u32 v71, v10, 4, 2
	v_lshlrev_b32_e32 v69, 4, v71
	v_add_u32_e32 v4, 0x200, v10
	v_ashrrev_i32_e32 v4, 4, v4
	v_mad_i64_i32 v[20:21], s[48:49], v4, s61, v[16:17]
	global_load_dwordx4 v[124:127], v[20:21], off
	v_mul_lo_u32 v29, v4, s65
	v_add_u32_e32 v30, v26, v29
	v_ashrrev_i32_e32 v5, 31, v4
	v_add_u32_e32 v6, 0x400, v10
	v_ashrrev_i32_e32 v6, 4, v6
	v_mad_i64_i32 v[22:23], s[48:49], v6, s61, v[16:17]
	global_load_dwordx4 v[128:131], v[22:23], off
	v_add_u32_e32 v8, 0x600, v10
	v_mul_lo_u32 v31, v6, s65
	v_ashrrev_i32_e32 v8, 4, v8
	v_add_u32_e32 v32, v26, v31
	v_mad_i64_i32 v[24:25], s[48:49], v8, s61, v[16:17]
	s_lshl_b64 s[48:49], s[92:93], 15
	s_add_u32 s40, s40, s48
	s_addc_u32 s41, s41, s49
	v_ashrrev_i32_e32 v7, 31, v6
	v_ashrrev_i32_e32 v9, 31, v8
	s_ashr_i32 s34, s22, 2
	s_mov_b32 s22, 0x800000
	v_cmp_gt_f32_e32 vcc, s22, v11
	s_and_b64 s[22:23], vcc, exec
	s_cselect_b32 s22, 32, 0
	v_bfi_b32 v66, -16, s34, v10
	global_load_dwordx4 v[132:135], v[24:25], off
	v_mul_lo_u32 v12, v8, s65
	v_add_u32_e32 v13, v26, v12
	v_mov_b32_e32 v119, v13
	global_load_dwordx4 v[136:139], v[18:19], off offset:1536
	global_load_dwordx4 v[140:143], v[20:21], off offset:1536
	global_load_dwordx4 v[144:147], v[22:23], off offset:1536
	global_load_dwordx4 v[148:151], v[24:25], off offset:1536
	v_and_b32_e32 v13, 0x7f, v10
	v_mul_u32_u24_e32 v14, 0x1900, v13
	v_lshlrev_b32_e32 v14, 1, v14
	v_mov_b32_e32 v15, v1
	v_lshl_add_u64 v[18:19], s[56:57], 0, v[14:15]
	v_and_b32_e32 v14, -8, v2
	v_ashrrev_i32_e32 v15, 31, v14
	v_lshl_add_u64 v[16:17], v[14:15], 1, v[18:19]
	v_mul_lo_u32 v14, v14, s65
	v_lshlrev_b32_e32 v13, 1, v13
	v_add3_u32 v20, s70, v14, v13
	global_load_dwordx4 v[152:155], v[16:17], off offset:3072
	v_lshlrev_b64 v[2:3], 8, v[2:3]
	v_mov_b32_e32 v156, v20
	v_and_b32_e32 v14, -8, v4
	v_ashrrev_i32_e32 v15, 31, v14
	v_lshl_add_u64 v[16:17], v[14:15], 1, v[18:19]
	v_mul_lo_u32 v14, v14, s65
	v_add3_u32 v20, s70, v14, v13
	global_load_dwordx4 v[158:161], v[16:17], off offset:3072
	v_mov_b32_e32 v157, v20
	v_and_b32_e32 v14, -8, v6
	v_ashrrev_i32_e32 v15, 31, v14
	v_lshl_add_u64 v[16:17], v[14:15], 1, v[18:19]
	v_mul_lo_u32 v14, v14, s65
	v_add3_u32 v20, s70, v14, v13
	global_load_dwordx4 v[162:165], v[16:17], off offset:3072
	v_and_b32_e32 v14, -8, v8
	v_ashrrev_i32_e32 v15, 31, v14
	v_lshl_add_u64 v[16:17], v[14:15], 1, v[18:19]
	v_mul_lo_u32 v14, v14, s65
	v_add3_u32 v13, s70, v14, v13
	global_load_dwordx4 v[166:169], v[16:17], off offset:3072
	v_mov_b32_e32 v170, v13
	v_lshl_add_u64 v[14:15], s[40:41], 0, v[0:1]
	s_mov_b64 s[40:41], 0x33600000
	v_lshl_add_u64 v[18:19], v[14:15], 0, s[40:41]
	v_lshl_add_u64 v[2:3], v[18:19], 0, v[2:3]
	global_load_dwordx4 v[172:175], v[2:3], off
	v_readlane_b32 s40, v255, 29
	s_nop 1
	v_add_u32_e32 v0, s40, v0
	v_add_u32_e32 v2, v0, v27
	v_add_u32_e32 v13, v0, v29
	v_mov_b32_e32 v171, v2
	v_lshlrev_b64 v[2:3], 8, v[4:5]
	v_lshl_add_u64 v[2:3], v[18:19], 0, v[2:3]
	global_load_dwordx4 v[176:179], v[2:3], off
	v_lshlrev_b64 v[2:3], 8, v[6:7]
	v_lshl_add_u64 v[2:3], v[18:19], 0, v[2:3]
	global_load_dwordx4 v[180:183], v[2:3], off
	v_add_u32_e32 v6, v0, v31
	v_add_u32_e32 v0, v0, v12
	v_lshlrev_b64 v[2:3], 8, v[8:9]
	v_lshl_add_u64 v[2:3], v[18:19], 0, v[2:3]
	global_load_dwordx4 v[184:187], v[2:3], off
	s_waitcnt vmcnt(15)
	ds_write_b128 v28, v[120:123]
	s_waitcnt vmcnt(14)
	ds_write_b128 v30, v[124:127]
	s_waitcnt vmcnt(13)
	ds_write_b128 v32, v[128:131]
	s_waitcnt vmcnt(12)
; #define LAS __attribute__((address_space(3)))
; #define ZERO8(a) do { _Pragma("unroll") for (int t_ = 0; t_ < 8; ++t_) a[t_] = (f32x4){0.f, 0.f, 0.f, 0.f}; } while (0)
; __device__ __forceinline__ void wave_mma(f32x4 (&acc)[8], const LAS bfu* As, const LAS bfu* Bs, int m0, int fr, int fq) {
; #pragma unroll
;     for (int ks = 0; ks < 4; ++ks) { const bf16x8 a = *(const LAS bf16x8*)(As + (m0 + fr) * TS + ks * 32 + fq * 8);
; #pragma unroll
;         for (int t = 0; t < 8; ++t) { const bf16x8 b = *(const LAS bf16x8*)(Bs + (t * 16 + fr) * TS + ks * 32 + fq * 8); acc[t] = __builtin_amdgcn_mfma_f32_16x16x32_bf16(b, a, acc[t], 0, 0, 0); } }
; }
; __device__ __forceinline__ void ret_unit(LAS unsigned char* lds, const bfu* PROJ, const bfu* RT, const float* gn_g, bfu* CAT, int u) {
;     ...
;     stage_nat(Qs, P0 + C_RQ, INW, tid); stage_nat(Ks, P0 + C_RK, INW, tid); stage_tr<false>(Vt, P0 + C_RV, INW, tid, 0.f); stage_nat(Rt, RT + (size_t)u * 16384, 128, tid);
;     __syncthreads();
;     const int fr = lane & 15, fq = lane >> 4, m0 = wid * 16, c = m0 + fr;
;     f32x4 acc[8], cr[8]; ZERO8(acc); ZERO8(cr);
;     wave_mma(cr, Qs, Rt, m0, fr, fq);
;     wave_mma(acc, Qs, Ks, m0, fr, fq);
	ds_write_b128 v119, v[132:135]
	s_waitcnt vmcnt(11)
	ds_write_b128 v28, v[136:139] offset:34816
	s_waitcnt vmcnt(10)
	ds_write_b128 v30, v[140:143] offset:34816
	s_waitcnt vmcnt(9)
	ds_write_b128 v32, v[144:147] offset:34816
	s_waitcnt vmcnt(8)
	ds_write_b128 v119, v[148:151] offset:34816
	s_waitcnt vmcnt(7)
	ds_write_b16 v156, v152
	ds_write_b16_d16_hi v156, v152 offset:272
	ds_write_b16 v156, v153 offset:544
	ds_write_b16_d16_hi v156, v153 offset:816
	ds_write_b16 v156, v154 offset:1088
	ds_write_b16_d16_hi v156, v154 offset:1360
	ds_write_b16 v156, v155 offset:1632
	ds_write_b16_d16_hi v156, v155 offset:1904
	s_waitcnt vmcnt(6)
	ds_write_b16 v157, v158
	ds_write_b16_d16_hi v157, v158 offset:272
	ds_write_b16 v157, v159 offset:544
	ds_write_b16_d16_hi v157, v159 offset:816
	ds_write_b16 v157, v160 offset:1088
	ds_write_b16_d16_hi v157, v160 offset:1360
	ds_write_b16 v157, v161 offset:1632
	ds_write_b16_d16_hi v157, v161 offset:1904
	s_waitcnt vmcnt(5)
	ds_write_b16 v20, v162
	ds_write_b16_d16_hi v20, v162 offset:272
	ds_write_b16 v20, v163 offset:544
	ds_write_b16_d16_hi v20, v163 offset:816
	ds_write_b16 v20, v164 offset:1088
	ds_write_b16_d16_hi v20, v164 offset:1360
	ds_write_b16 v20, v165 offset:1632
	ds_write_b16_d16_hi v20, v165 offset:1904
	s_waitcnt vmcnt(4)
	ds_write_b16 v170, v166
	ds_write_b16_d16_hi v170, v166 offset:272
	ds_write_b16 v170, v167 offset:544
	ds_write_b16_d16_hi v170, v167 offset:816
	ds_write_b16 v170, v168 offset:1088
	ds_write_b16_d16_hi v170, v168 offset:1360
	ds_write_b16 v170, v169 offset:1632
	ds_write_b16_d16_hi v170, v169 offset:1904
	s_waitcnt vmcnt(3)
	ds_write_b128 v171, v[172:175]
	s_waitcnt vmcnt(2)
	ds_write_b128 v13, v[176:179]
	s_waitcnt vmcnt(1)
	ds_write_b128 v6, v[180:183]
	s_waitcnt vmcnt(0)
	ds_write_b128 v0, v[184:187]
	v_ldexp_f32 v0, v11, s22
	v_log_f32_e32 v0, v0
	v_cndmask_b32_e32 v2, 0, v242, vcc
	s_waitcnt lgkmcnt(0)
	s_barrier
	v_sub_f32_e32 v67, v0, v2
	v_and_b32_e32 v2, 15, v10
	v_mul_lo_u32 v0, v66, s65
	v_add_u32_e32 v73, 0, v0
	v_mul_u32_u24_e32 v70, 0x110, v2
	v_add_u32_e32 v62, v73, v69
	v_add3_u32 v63, s40, v69, v70
	ds_read_b128 v[46:49], v62
	ds_read_b128 v[2:5], v63
	ds_read_b128 v[6:9], v63 offset:4352
	ds_read_b128 v[10:13], v63 offset:8704
	ds_read_b128 v[14:17], v63 offset:13056
	ds_read_b128 v[18:21], v63 offset:17408
	ds_read_b128 v[22:25], v63 offset:21760
	ds_read_b128 v[26:29], v63 offset:26112
	ds_read_b128 v[30:33], v63 offset:30464
	ds_read_b128 v[38:41], v62 offset:64
	ds_read_b128 v[34:37], v63 offset:64
	s_waitcnt lgkmcnt(9)
	v_mfma_f32_16x16x32_bf16 v[2:5], v[2:5], v[46:49], 0
	v_add3_u32 v72, 0, v69, v70
	v_lshlrev_b32_e32 v0, 3, v71
	s_waitcnt lgkmcnt(0)
	v_mfma_f32_16x16x32_bf16 v[2:5], v[34:37], v[38:41], v[2:5]
	ds_read_b128 v[34:37], v63 offset:4416
	v_mfma_f32_16x16x32_bf16 v[6:9], v[6:9], v[46:49], 0
	s_waitcnt lgkmcnt(0)
	v_mfma_f32_16x16x32_bf16 v[6:9], v[34:37], v[38:41], v[6:9]
	ds_read_b128 v[34:37], v63 offset:8768
	v_mfma_f32_16x16x32_bf16 v[10:13], v[10:13], v[46:49], 0
	s_waitcnt lgkmcnt(0)
	v_mfma_f32_16x16x32_bf16 v[10:13], v[34:37], v[38:41], v[10:13]
	ds_read_b128 v[34:37], v63 offset:13120
	v_mfma_f32_16x16x32_bf16 v[14:17], v[14:17], v[46:49], 0
	s_waitcnt lgkmcnt(0)
	v_mfma_f32_16x16x32_bf16 v[14:17], v[34:37], v[38:41], v[14:17]
	ds_read_b128 v[34:37], v63 offset:17472
	v_mfma_f32_16x16x32_bf16 v[18:21], v[18:21], v[46:49], 0
	s_waitcnt lgkmcnt(0)
	v_mfma_f32_16x16x32_bf16 v[18:21], v[34:37], v[38:41], v[18:21]
	ds_read_b128 v[34:37], v63 offset:21824
	v_mfma_f32_16x16x32_bf16 v[22:25], v[22:25], v[46:49], 0
	s_waitcnt lgkmcnt(0)
	v_mfma_f32_16x16x32_bf16 v[22:25], v[34:37], v[38:41], v[22:25]
	ds_read_b128 v[34:37], v63 offset:26176
	v_mfma_f32_16x16x32_bf16 v[26:29], v[26:29], v[46:49], 0
	s_waitcnt lgkmcnt(0)
	v_mfma_f32_16x16x32_bf16 v[26:29], v[34:37], v[38:41], v[26:29]
	ds_read_b128 v[34:37], v63 offset:30528
	v_mfma_f32_16x16x32_bf16 v[30:33], v[30:33], v[46:49], 0
	s_waitcnt lgkmcnt(0)
	v_mfma_f32_16x16x32_bf16 v[30:33], v[34:37], v[38:41], v[30:33]
	ds_read_b128 v[42:45], v62 offset:128
	ds_read_b128 v[34:37], v63 offset:128
	s_waitcnt lgkmcnt(0)
	v_mfma_f32_16x16x32_bf16 v[2:5], v[34:37], v[42:45], v[2:5]
	ds_read_b128 v[34:37], v63 offset:4480
	s_waitcnt lgkmcnt(0)
	v_mfma_f32_16x16x32_bf16 v[6:9], v[34:37], v[42:45], v[6:9]
	ds_read_b128 v[34:37], v63 offset:8832
	s_waitcnt lgkmcnt(0)
	v_mfma_f32_16x16x32_bf16 v[50:53], v[34:37], v[42:45], v[10:13]
	s_nop 2
	ds_read_b128 v[10:13], v63 offset:13184
	s_waitcnt lgkmcnt(0)
	v_mfma_f32_16x16x32_bf16 v[14:17], v[10:13], v[42:45], v[14:17]
	ds_read_b128 v[10:13], v63 offset:17536
	s_waitcnt lgkmcnt(0)
	v_mfma_f32_16x16x32_bf16 v[18:21], v[10:13], v[42:45], v[18:21]
	ds_read_b128 v[10:13], v63 offset:21888
	s_waitcnt lgkmcnt(0)
	v_mfma_f32_16x16x32_bf16 v[22:25], v[10:13], v[42:45], v[22:25]
	ds_read_b128 v[10:13], v63 offset:26240
	s_waitcnt lgkmcnt(0)
	v_mfma_f32_16x16x32_bf16 v[54:57], v[10:13], v[42:45], v[26:29]
	ds_read_b128 v[10:13], v63 offset:30592
	s_waitcnt lgkmcnt(0)
	v_mfma_f32_16x16x32_bf16 v[58:61], v[10:13], v[42:45], v[30:33]
	ds_read_b128 v[34:37], v62 offset:192
	ds_read_b128 v[10:13], v63 offset:192
	ds_read_b128 v[74:77], v72 offset:52224
	ds_read_b128 v[78:81], v72 offset:56576
	ds_read_b128 v[82:85], v72 offset:60928
	s_waitcnt lgkmcnt(3)
	v_mfma_f32_16x16x32_bf16 v[10:13], v[10:13], v[34:37], v[2:5]
	ds_read_b128 v[86:89], v72 offset:65280
	s_nop 1
	ds_read_b128 v[2:5], v63 offset:4544
	s_waitcnt lgkmcnt(0)
	v_mfma_f32_16x16x32_bf16 v[30:33], v[2:5], v[34:37], v[6:9]
	ds_read_b128 v[2:5], v63 offset:8896
	s_nop 1
	ds_read_b128 v[6:9], v63 offset:13248
	s_waitcnt lgkmcnt(0)
; __device__ __forceinline__ float fexp2(float x) { return __builtin_amdgcn_exp2f(x); }
; __device__ __forceinline__ void ret_unit(LAS unsigned char* lds, const bfu* PROJ, const bfu* RT, const float* gn_g, bfu* CAT, int u) {
;     ...
;     wave_mma(cr, Qs, Rt, m0, fr, fq);
;     wave_mma(acc, Qs, Ks, m0, fr, fq);
;     __syncthreads();
; #pragma unroll
;     for (int t = 0; t < 8; ++t) { float p[4];
; #pragma unroll
;         for (int j = 0; j < 4; ++j) { const int e = 16 * t + 4 * fq + j; p[j] = (c >= e) ? acc[t][j] * fexp2(lg * (float)(c - e)) : 0.f; }
	v_mfma_f32_16x16x32_bf16 v[14:17], v[6:9], v[34:37], v[14:17]
	ds_read_b128 v[6:9], v63 offset:17600
	v_mfma_f32_16x16x32_bf16 v[2:5], v[2:5], v[34:37], v[50:53]
	s_nop 2
	ds_read_b128 v[50:53], v72 offset:34816
	s_waitcnt lgkmcnt(1)
	v_mfma_f32_16x16x32_bf16 v[26:29], v[6:9], v[34:37], v[18:21]
	ds_read_b128 v[6:9], v63 offset:21952
	s_nop 1
	ds_read_b128 v[18:21], v63 offset:26304
	s_waitcnt lgkmcnt(1)
	v_mfma_f32_16x16x32_bf16 v[6:9], v[6:9], v[34:37], v[22:25]
	s_nop 2
	ds_read_b128 v[22:25], v63 offset:30656
	s_waitcnt lgkmcnt(1)
	v_mfma_f32_16x16x32_bf16 v[18:21], v[18:21], v[34:37], v[54:57]
	s_nop 2
	ds_read_b128 v[54:57], v72 offset:39168
	s_waitcnt lgkmcnt(1)
	v_mfma_f32_16x16x32_bf16 v[22:25], v[22:25], v[34:37], v[58:61]
	ds_read_b128 v[62:65], v72 offset:47872
	s_nop 1
	ds_read_b128 v[58:61], v72 offset:43520
	v_mfma_f32_16x16x32_bf16 v[50:53], v[50:53], v[46:49], 0
	s_waitcnt lgkmcnt(2)
	v_mfma_f32_16x16x32_bf16 v[54:57], v[54:57], v[46:49], 0
	s_waitcnt lgkmcnt(0)
	v_mfma_f32_16x16x32_bf16 v[58:61], v[58:61], v[46:49], 0
	v_mfma_f32_16x16x32_bf16 v[62:65], v[62:65], v[46:49], 0
	v_mfma_f32_16x16x32_bf16 v[74:77], v[74:77], v[46:49], 0
	v_mfma_f32_16x16x32_bf16 v[78:81], v[78:81], v[46:49], 0
	v_mfma_f32_16x16x32_bf16 v[82:85], v[82:85], v[46:49], 0
	v_mfma_f32_16x16x32_bf16 v[46:49], v[86:89], v[46:49], 0
	ds_read_b128 v[86:89], v72 offset:34880
	s_waitcnt lgkmcnt(0)
	v_mfma_f32_16x16x32_bf16 v[50:53], v[86:89], v[38:41], v[50:53]
	ds_read_b128 v[86:89], v72 offset:39232
	s_waitcnt lgkmcnt(0)
	v_mfma_f32_16x16x32_bf16 v[54:57], v[86:89], v[38:41], v[54:57]
	ds_read_b128 v[86:89], v72 offset:43584
	s_waitcnt lgkmcnt(0)
	v_mfma_f32_16x16x32_bf16 v[58:61], v[86:89], v[38:41], v[58:61]
	ds_read_b128 v[86:89], v72 offset:47936
	s_waitcnt lgkmcnt(0)
	v_mfma_f32_16x16x32_bf16 v[62:65], v[86:89], v[38:41], v[62:65]
	ds_read_b128 v[86:89], v72 offset:52288
	s_waitcnt lgkmcnt(0)
	v_mfma_f32_16x16x32_bf16 v[74:77], v[86:89], v[38:41], v[74:77]
	ds_read_b128 v[86:89], v72 offset:56640
	s_waitcnt lgkmcnt(0)
	v_mfma_f32_16x16x32_bf16 v[78:81], v[86:89], v[38:41], v[78:81]
	ds_read_b128 v[86:89], v72 offset:60992
	s_waitcnt lgkmcnt(0)
	v_mfma_f32_16x16x32_bf16 v[82:85], v[86:89], v[38:41], v[82:85]
	ds_read_b128 v[86:89], v72 offset:65344
	s_waitcnt lgkmcnt(0)
	v_mfma_f32_16x16x32_bf16 v[38:41], v[86:89], v[38:41], v[46:49]
	s_nop 2
	ds_read_b128 v[46:49], v72 offset:34944
	s_waitcnt lgkmcnt(0)
	v_mfma_f32_16x16x32_bf16 v[46:49], v[46:49], v[42:45], v[50:53]
	s_nop 2
	ds_read_b128 v[50:53], v72 offset:39296
	s_waitcnt lgkmcnt(0)
	v_mfma_f32_16x16x32_bf16 v[50:53], v[50:53], v[42:45], v[54:57]
	s_nop 2
	ds_read_b128 v[54:57], v72 offset:43648
	s_waitcnt lgkmcnt(0)
	v_mfma_f32_16x16x32_bf16 v[54:57], v[54:57], v[42:45], v[58:61]
	s_nop 2
	ds_read_b128 v[58:61], v72 offset:48000
	s_waitcnt lgkmcnt(0)
	v_mfma_f32_16x16x32_bf16 v[86:89], v[58:61], v[42:45], v[62:65]
	ds_read_b128 v[58:61], v72 offset:52352
	s_waitcnt lgkmcnt(0)
	v_mfma_f32_16x16x32_bf16 v[74:77], v[58:61], v[42:45], v[74:77]
	ds_read_b128 v[58:61], v72 offset:56704
	s_waitcnt lgkmcnt(0)
	v_mfma_f32_16x16x32_bf16 v[78:81], v[58:61], v[42:45], v[78:81]
	ds_read_b128 v[58:61], v72 offset:61056
	s_waitcnt lgkmcnt(0)
	v_mfma_f32_16x16x32_bf16 v[82:85], v[58:61], v[42:45], v[82:85]
	ds_read_b128 v[58:61], v72 offset:65408
	s_waitcnt lgkmcnt(0)
	v_mfma_f32_16x16x32_bf16 v[90:93], v[58:61], v[42:45], v[38:41]
	s_nop 2
	ds_read_b128 v[38:41], v72 offset:35008
	s_waitcnt lgkmcnt(0)
	v_mfma_f32_16x16x32_bf16 v[62:65], v[38:41], v[34:37], v[46:49]
	ds_read_b128 v[38:41], v72 offset:39360
	s_waitcnt lgkmcnt(0)
	v_mfma_f32_16x16x32_bf16 v[58:61], v[38:41], v[34:37], v[50:53]
	ds_read_b128 v[38:41], v72 offset:43712
	s_waitcnt lgkmcnt(0)
	v_mfma_f32_16x16x32_bf16 v[54:57], v[38:41], v[34:37], v[54:57]
	ds_read_b128 v[38:41], v72 offset:48064
	s_waitcnt lgkmcnt(0)
	v_mfma_f32_16x16x32_bf16 v[50:53], v[38:41], v[34:37], v[86:89]
	ds_read_b128 v[38:41], v72 offset:52416
	s_waitcnt lgkmcnt(0)
	v_mfma_f32_16x16x32_bf16 v[46:49], v[38:41], v[34:37], v[74:77]
	ds_read_b128 v[38:41], v72 offset:56768
	s_nop 1
	ds_read_b128 v[74:77], v72 offset:65472
	s_waitcnt lgkmcnt(1)
	v_mfma_f32_16x16x32_bf16 v[42:45], v[38:41], v[34:37], v[78:81]
	ds_read_b128 v[38:41], v72 offset:61120
	v_lshlrev_b32_e32 v72, 2, v71
	v_add_u32_e32 v71, v73, v0
	v_sub_u32_e32 v73, v66, v72
	v_cvt_f32_i32_e32 v73, v73
	v_cmp_ge_i32_e32 vcc, v66, v72
	s_waitcnt lgkmcnt(0)
	v_mfma_f32_16x16x32_bf16 v[38:41], v[38:41], v[34:37], v[82:85]
	v_mul_f32_e32 v73, v67, v73
	v_exp_f32_e32 v73, v73
	v_mfma_f32_16x16x32_bf16 v[34:37], v[74:77], v[34:37], v[90:93]
	v_or_b32_e32 v75, 3, v72
	v_mul_f32_e32 v62, v73, v62
	v_cndmask_b32_e32 v73, 0, v62, vcc
	v_xad_u32 v62, v72, -1, v66
	v_cvt_f32_i32_e32 v62, v62
	v_cmp_gt_i32_e32 vcc, v66, v72
	v_or_b32_e32 v76, 2, v72
	s_barrier
; #define LAS __attribute__((address_space(3)))
; __device__ __forceinline__ unsigned pk2(float lo, float hi) { return pg8::cvt_pk_bf16(lo, hi); }
; __device__ __forceinline__ float fexp2(float x) { return __builtin_amdgcn_exp2f(x); }
; __device__ __forceinline__ void ret_unit(LAS unsigned char* lds, const bfu* PROJ, const bfu* RT, const float* gn_g, bfu* CAT, int u) {
;     ...
;     for (int t = 0; t < 8; ++t) { float p[4];
; #pragma unroll
;         for (int j = 0; j < 4; ++j) { const int e = 16 * t + 4 * fq + j; p[j] = (c >= e) ? acc[t][j] * fexp2(lg * (float)(c - e)) : 0.f; }
;         v2u w; w.x = pk2(p[0], p[1]); w.y = pk2(p[2], p[3]); *(LAS v2u*)(Ks + c * TS + 16 * t + 4 * fq) = w; }
	v_mul_f32_e32 v62, v67, v62
	v_exp_f32_e32 v62, v62
	v_add_u32_e32 v78, v71, v0
	v_add3_u32 v82, s70, v69, v70
	v_mul_f32_e32 v62, v62, v63
	v_cndmask_b32_e32 v74, 0, v62, vcc
	v_sub_u32_e32 v62, v66, v76
	v_sub_u32_e32 v63, v66, v75
	v_cvt_f32_i32_e32 v62, v62
	v_cvt_f32_i32_e32 v63, v63
	v_cmp_ge_i32_e32 vcc, v66, v76
	v_or_b32_e32 v76, 18, v72
	v_mul_f32_e32 v62, v67, v62
	v_mul_f32_e32 v63, v67, v63
	v_exp_f32_e32 v62, v62
	v_exp_f32_e32 v63, v63
	s_nop 0
	v_pk_mul_f32 v[62:63], v[62:63], v[64:65]
	s_nop 0
	v_cvt_pk_bf16_f32 v62, v62, v63
	v_cndmask_b32_e32 v63, 0, v62, vcc
	v_lshrrev_b32_e32 v62, 16, v62
	v_cmp_ge_i32_e32 vcc, v66, v75
	v_cvt_pk_bf16_f32 v64, v73, v74
	v_or_b32_e32 v73, 17, v72
	v_cndmask_b32_e32 v62, 0, v62, vcc
	v_or_b32_e32 v74, 16, v72
	v_perm_b32 v65, v62, v63, s72
	v_sub_u32_e32 v62, v66, v74
	v_sub_u32_e32 v63, v66, v73
	v_cvt_f32_i32_e32 v62, v62
	v_cvt_f32_i32_e32 v63, v63
	v_or_b32_e32 v75, 19, v72
	v_cmp_ge_i32_e32 vcc, v66, v74
	v_mul_f32_e32 v62, v67, v62
	v_mul_f32_e32 v63, v67, v63
	v_exp_f32_e32 v62, v62
	v_exp_f32_e32 v63, v63
	s_nop 0
	v_pk_mul_f32 v[58:59], v[62:63], v[58:59]
	v_sub_u32_e32 v62, v66, v76
	v_sub_u32_e32 v63, v66, v75
	v_cvt_f32_i32_e32 v62, v62
	v_cvt_f32_i32_e32 v63, v63
	v_cvt_pk_bf16_f32 v58, v58, v59
	v_cndmask_b32_e32 v59, 0, v58, vcc
	v_mul_f32_e32 v62, v67, v62
	v_mul_f32_e32 v63, v67, v63
	v_exp_f32_e32 v62, v62
	v_exp_f32_e32 v63, v63
	v_lshrrev_b32_e32 v58, 16, v58
	v_cmp_ge_i32_e32 vcc, v66, v73
	v_pk_mul_f32 v[60:61], v[62:63], v[60:61]
	s_nop 0
	v_cndmask_b32_e32 v58, 0, v58, vcc
	v_perm_b32 v62, v58, v59, s72
	v_cvt_pk_bf16_f32 v58, v60, v61
	v_cmp_ge_i32_e32 vcc, v66, v76
	s_nop 1
	v_cndmask_b32_e32 v59, 0, v58, vcc
	v_lshrrev_b32_e32 v58, 16, v58
	v_cmp_ge_i32_e32 vcc, v66, v75
	s_nop 1
	v_cndmask_b32_e32 v58, 0, v58, vcc
	v_perm_b32 v63, v58, v59, s72
	v_add_u32_e32 v58, 0x8800, v71
	ds_write2_b64 v58, v[64:65], v[62:63] offset1:4
	v_or_b32_e32 v59, 33, v72
	v_or_b32_e32 v62, 32, v72
	v_sub_u32_e32 v60, v66, v62
	v_sub_u32_e32 v61, v66, v59
	v_cvt_f32_i32_e32 v60, v60
	v_cvt_f32_i32_e32 v61, v61
	v_or_b32_e32 v63, 35, v72
	v_or_b32_e32 v64, 34, v72
	v_mul_f32_e32 v60, v67, v60
	v_mul_f32_e32 v61, v67, v61
	v_exp_f32_e32 v60, v60
	v_exp_f32_e32 v61, v61
	v_cmp_ge_i32_e32 vcc, v66, v62
	v_or_b32_e32 v62, 50, v72
	v_pk_mul_f32 v[54:55], v[60:61], v[54:55]
	v_sub_u32_e32 v60, v66, v64
	v_sub_u32_e32 v61, v66, v63
	v_cvt_f32_i32_e32 v60, v60
	v_cvt_f32_i32_e32 v61, v61
	v_cvt_pk_bf16_f32 v54, v54, v55
	v_cndmask_b32_e32 v55, 0, v54, vcc
	v_mul_f32_e32 v60, v67, v60
	v_mul_f32_e32 v61, v67, v61
	v_exp_f32_e32 v60, v60
	v_exp_f32_e32 v61, v61
	v_lshrrev_b32_e32 v54, 16, v54
	v_cmp_ge_i32_e32 vcc, v66, v59
	v_or_b32_e32 v59, 49, v72
	v_pk_mul_f32 v[56:57], v[60:61], v[56:57]
	v_cndmask_b32_e32 v54, 0, v54, vcc
	v_perm_b32 v54, v54, v55, s72
	v_cvt_pk_bf16_f32 v55, v56, v57
	v_cmp_ge_i32_e32 vcc, v66, v64
	v_or_b32_e32 v60, 48, v72
	v_sub_u32_e32 v57, v66, v59
	v_cndmask_b32_e32 v56, 0, v55, vcc
	v_lshrrev_b32_e32 v55, 16, v55
	v_cmp_ge_i32_e32 vcc, v66, v63
	v_cvt_f32_i32_e32 v57, v57
	v_or_b32_e32 v61, 51, v72
	v_cndmask_b32_e32 v55, 0, v55, vcc
	v_perm_b32 v55, v55, v56, s72
	v_sub_u32_e32 v56, v66, v60
	v_cvt_f32_i32_e32 v56, v56
	v_mul_f32_e32 v57, v67, v57
	v_exp_f32_e32 v57, v57
	v_cmp_ge_i32_e32 vcc, v66, v60
	v_mul_f32_e32 v56, v67, v56
	v_exp_f32_e32 v56, v56
	s_nop 0
	v_pk_mul_f32 v[50:51], v[56:57], v[50:51]
	v_sub_u32_e32 v56, v66, v62
	v_sub_u32_e32 v57, v66, v61
	v_cvt_f32_i32_e32 v56, v56
	v_cvt_f32_i32_e32 v57, v57
	v_cvt_pk_bf16_f32 v50, v50, v51
	v_cndmask_b32_e32 v51, 0, v50, vcc
	v_mul_f32_e32 v56, v67, v56
	v_mul_f32_e32 v57, v67, v57
	v_exp_f32_e32 v56, v56
	v_exp_f32_e32 v57, v57
	v_lshrrev_b32_e32 v50, 16, v50
	v_cmp_ge_i32_e32 vcc, v66, v59
	v_pk_mul_f32 v[52:53], v[56:57], v[52:53]
	s_nop 0
	v_cndmask_b32_e32 v50, 0, v50, vcc
	v_perm_b32 v50, v50, v51, s72
	v_cvt_pk_bf16_f32 v51, v52, v53
	v_cmp_ge_i32_e32 vcc, v66, v62
	v_or_b32_e32 v53, 64, v72
	s_nop 0
	v_cndmask_b32_e32 v52, 0, v51, vcc
	v_lshrrev_b32_e32 v51, 16, v51
	v_cmp_ge_i32_e32 vcc, v66, v61
	s_nop 1
	v_cndmask_b32_e32 v51, 0, v51, vcc
	v_perm_b32 v51, v51, v52, s72
	v_or_b32_e32 v52, 0x41, v72
	ds_write2_b64 v58, v[54:55], v[50:51] offset0:8 offset1:12
	v_sub_u32_e32 v50, v66, v53
	v_sub_u32_e32 v51, v66, v52
	v_cvt_f32_i32_e32 v50, v50
	v_cvt_f32_i32_e32 v51, v51
	v_or_b32_e32 v54, 0x43, v72
	v_or_b32_e32 v55, 0x42, v72
	v_mul_f32_e32 v50, v67, v50
	v_mul_f32_e32 v51, v67, v51
	v_exp_f32_e32 v50, v50
	v_exp_f32_e32 v51, v51
	v_cmp_ge_i32_e32 vcc, v66, v53
	v_or_b32_e32 v53, 0x52, v72
	v_pk_mul_f32 v[46:47], v[50:51], v[46:47]
	v_sub_u32_e32 v50, v66, v55
	v_sub_u32_e32 v51, v66, v54
	v_cvt_f32_i32_e32 v50, v50
	v_cvt_f32_i32_e32 v51, v51
	v_cvt_pk_bf16_f32 v46, v46, v47
	v_cndmask_b32_e32 v47, 0, v46, vcc
	v_mul_f32_e32 v50, v67, v50
	v_mul_f32_e32 v51, v67, v51
	v_exp_f32_e32 v50, v50
	v_exp_f32_e32 v51, v51
	v_lshrrev_b32_e32 v46, 16, v46
	v_cmp_ge_i32_e32 vcc, v66, v52
	v_or_b32_e32 v52, 0x53, v72
	v_pk_mul_f32 v[48:49], v[50:51], v[48:49]
	v_cndmask_b32_e32 v46, 0, v46, vcc
	v_perm_b32 v46, v46, v47, s72
	v_cvt_pk_bf16_f32 v47, v48, v49
	v_cmp_ge_i32_e32 vcc, v66, v55
	v_or_b32_e32 v50, 0x51, v72
	v_or_b32_e32 v51, 0x50, v72
	v_cndmask_b32_e32 v48, 0, v47, vcc
	v_lshrrev_b32_e32 v47, 16, v47
	v_cmp_ge_i32_e32 vcc, v66, v54
	v_sub_u32_e32 v49, v66, v50
	v_cvt_f32_i32_e32 v49, v49
	v_cndmask_b32_e32 v47, 0, v47, vcc
	v_perm_b32 v47, v47, v48, s72
	v_sub_u32_e32 v48, v66, v51
	v_cvt_f32_i32_e32 v48, v48
	v_mul_f32_e32 v49, v67, v49
	v_exp_f32_e32 v49, v49
	v_cmp_ge_i32_e32 vcc, v66, v51
; #define LAS __attribute__((address_space(3)))
; #define LDS_WAIT() asm volatile("s_waitcnt lgkmcnt(0)" ::: "memory")
; __device__ __forceinline__ unsigned pk2(float lo, float hi) { return pg8::cvt_pk_bf16(lo, hi); }
; __device__ __forceinline__ float fexp2(float x) { return __builtin_amdgcn_exp2f(x); }
; #define ZERO8(a) do { _Pragma("unroll") for (int t_ = 0; t_ < 8; ++t_) a[t_] = (f32x4){0.f, 0.f, 0.f, 0.f}; } while (0)
; __device__ __forceinline__ void ret_unit(LAS unsigned char* lds, const bfu* PROJ, const bfu* RT, const float* gn_g, bfu* CAT, int u) {
;     ...
;     for (int t = 0; t < 8; ++t) { float p[4];
; #pragma unroll
;         for (int j = 0; j < 4; ++j) { const int e = 16 * t + 4 * fq + j; p[j] = (c >= e) ? acc[t][j] * fexp2(lg * (float)(c - e)) : 0.f; }
;         v2u w; w.x = pk2(p[0], p[1]); w.y = pk2(p[2], p[3]); *(LAS v2u*)(Ks + c * TS + 16 * t + 4 * fq) = w; }
;     LDS_WAIT(); asm volatile("" ::: "memory");
;     ZERO8(acc);
;     wave_mma(acc, Ks, Vt, m0, fr, fq);
	v_mul_f32_e32 v48, v67, v48
	v_exp_f32_e32 v48, v48
	s_nop 0
	v_pk_mul_f32 v[42:43], v[48:49], v[42:43]
	v_sub_u32_e32 v48, v66, v53
	v_sub_u32_e32 v49, v66, v52
	v_cvt_f32_i32_e32 v48, v48
	v_cvt_f32_i32_e32 v49, v49
	v_cvt_pk_bf16_f32 v42, v42, v43
	v_cndmask_b32_e32 v43, 0, v42, vcc
	v_mul_f32_e32 v48, v67, v48
	v_mul_f32_e32 v49, v67, v49
	v_exp_f32_e32 v48, v48
	v_exp_f32_e32 v49, v49
	v_lshrrev_b32_e32 v42, 16, v42
	v_cmp_ge_i32_e32 vcc, v66, v50
	v_pk_mul_f32 v[44:45], v[48:49], v[44:45]
	s_nop 0
	v_cndmask_b32_e32 v42, 0, v42, vcc
	v_perm_b32 v42, v42, v43, s72
	v_cvt_pk_bf16_f32 v43, v44, v45
	v_cmp_ge_i32_e32 vcc, v66, v53
	v_or_b32_e32 v45, 0x60, v72
	s_nop 0
	v_cndmask_b32_e32 v44, 0, v43, vcc
	v_lshrrev_b32_e32 v43, 16, v43
	v_cmp_ge_i32_e32 vcc, v66, v52
	s_nop 1
	v_cndmask_b32_e32 v43, 0, v43, vcc
	v_perm_b32 v43, v43, v44, s72
	v_or_b32_e32 v44, 0x61, v72
	ds_write2_b64 v58, v[46:47], v[42:43] offset0:16 offset1:20
	v_sub_u32_e32 v42, v66, v45
	v_sub_u32_e32 v43, v66, v44
	v_cvt_f32_i32_e32 v42, v42
	v_cvt_f32_i32_e32 v43, v43
	v_or_b32_e32 v46, 0x63, v72
	v_or_b32_e32 v47, 0x62, v72
	v_mul_f32_e32 v42, v67, v42
	v_mul_f32_e32 v43, v67, v43
	v_exp_f32_e32 v42, v42
	v_exp_f32_e32 v43, v43
	v_cmp_ge_i32_e32 vcc, v66, v45
	v_or_b32_e32 v45, 0x72, v72
	v_pk_mul_f32 v[38:39], v[42:43], v[38:39]
	v_sub_u32_e32 v42, v66, v47
	v_sub_u32_e32 v43, v66, v46
	v_cvt_f32_i32_e32 v42, v42
	v_cvt_f32_i32_e32 v43, v43
	v_cvt_pk_bf16_f32 v38, v38, v39
	v_cndmask_b32_e32 v39, 0, v38, vcc
	v_mul_f32_e32 v42, v67, v42
	v_mul_f32_e32 v43, v67, v43
	v_exp_f32_e32 v42, v42
	v_exp_f32_e32 v43, v43
	v_lshrrev_b32_e32 v38, 16, v38
	v_cmp_ge_i32_e32 vcc, v66, v44
	v_or_b32_e32 v44, 0x73, v72
	v_pk_mul_f32 v[40:41], v[42:43], v[40:41]
	v_cndmask_b32_e32 v38, 0, v38, vcc
	v_perm_b32 v38, v38, v39, s72
	v_cvt_pk_bf16_f32 v39, v40, v41
	v_cmp_ge_i32_e32 vcc, v66, v47
	v_or_b32_e32 v42, 0x71, v72
	v_or_b32_e32 v43, 0x70, v72
	v_cndmask_b32_e32 v40, 0, v39, vcc
	v_lshrrev_b32_e32 v39, 16, v39
	v_cmp_ge_i32_e32 vcc, v66, v46
	v_sub_u32_e32 v41, v66, v42
	v_cvt_f32_i32_e32 v41, v41
	v_cndmask_b32_e32 v39, 0, v39, vcc
	v_perm_b32 v39, v39, v40, s72
	v_sub_u32_e32 v40, v66, v43
	v_cvt_f32_i32_e32 v40, v40
	v_mul_f32_e32 v41, v67, v41
	v_exp_f32_e32 v41, v41
	v_cmp_ge_i32_e32 vcc, v66, v43
	v_mul_f32_e32 v40, v67, v40
	v_exp_f32_e32 v40, v40
	s_nop 0
	v_pk_mul_f32 v[34:35], v[40:41], v[34:35]
	v_sub_u32_e32 v40, v66, v45
	v_sub_u32_e32 v41, v66, v44
	v_cvt_f32_i32_e32 v40, v40
	v_cvt_f32_i32_e32 v41, v41
	v_cvt_pk_bf16_f32 v34, v34, v35
	v_cndmask_b32_e32 v35, 0, v34, vcc
	v_mul_f32_e32 v40, v67, v40
	v_mul_f32_e32 v41, v67, v41
	v_exp_f32_e32 v40, v40
	v_exp_f32_e32 v41, v41
	v_lshrrev_b32_e32 v34, 16, v34
	v_cmp_ge_i32_e32 vcc, v66, v42
	v_pk_mul_f32 v[36:37], v[40:41], v[36:37]
	s_nop 0
	v_cndmask_b32_e32 v34, 0, v34, vcc
	v_perm_b32 v34, v34, v35, s72
	v_cvt_pk_bf16_f32 v35, v36, v37
	v_cmp_ge_i32_e32 vcc, v66, v45
	s_nop 1
	v_cndmask_b32_e32 v36, 0, v35, vcc
	v_lshrrev_b32_e32 v35, 16, v35
	v_cmp_ge_i32_e32 vcc, v66, v44
	s_nop 1
	v_cndmask_b32_e32 v35, 0, v35, vcc
	v_perm_b32 v35, v35, v36, s72
	ds_write2_b64 v58, v[38:39], v[34:35] offset0:24 offset1:28
	s_waitcnt lgkmcnt(0)
	ds_read_b128 v[34:37], v78 offset:34816
	ds_read_b128 v[38:41], v82
	ds_read_b128 v[42:45], v82 offset:4352
	ds_read_b128 v[46:49], v82 offset:8704
	ds_read_b128 v[50:53], v82 offset:13056
	ds_read_b128 v[54:57], v82 offset:17408
	ds_read_b128 v[58:61], v82 offset:21760
	ds_read_b128 v[62:65], v82 offset:26112
	ds_read_b128 v[70:73], v82 offset:30464
	s_waitcnt lgkmcnt(7)
	v_mfma_f32_16x16x32_bf16 v[38:41], v[38:41], v[34:37], 0
	s_waitcnt lgkmcnt(6)
	v_mfma_f32_16x16x32_bf16 v[42:45], v[42:45], v[34:37], 0
	s_waitcnt lgkmcnt(5)
	v_mfma_f32_16x16x32_bf16 v[46:49], v[46:49], v[34:37], 0
	s_waitcnt lgkmcnt(4)
	v_mfma_f32_16x16x32_bf16 v[50:53], v[50:53], v[34:37], 0
	s_waitcnt lgkmcnt(3)
	v_mfma_f32_16x16x32_bf16 v[54:57], v[54:57], v[34:37], 0
	s_waitcnt lgkmcnt(2)
	v_mfma_f32_16x16x32_bf16 v[58:61], v[58:61], v[34:37], 0
	s_waitcnt lgkmcnt(1)
	v_mfma_f32_16x16x32_bf16 v[62:65], v[62:65], v[34:37], 0
	s_waitcnt lgkmcnt(0)
	v_mfma_f32_16x16x32_bf16 v[34:37], v[70:73], v[34:37], 0
	ds_read_b128 v[70:73], v78 offset:34880
	ds_read_b128 v[74:77], v82 offset:64
	s_waitcnt lgkmcnt(0)
	v_mfma_f32_16x16x32_bf16 v[38:41], v[74:77], v[70:73], v[38:41]
	ds_read_b128 v[74:77], v82 offset:4416
	s_waitcnt lgkmcnt(0)
	v_mfma_f32_16x16x32_bf16 v[42:45], v[74:77], v[70:73], v[42:45]
	ds_read_b128 v[74:77], v82 offset:8768
	s_waitcnt lgkmcnt(0)
	v_mfma_f32_16x16x32_bf16 v[46:49], v[74:77], v[70:73], v[46:49]
	ds_read_b128 v[74:77], v82 offset:13120
	s_waitcnt lgkmcnt(0)
	v_mfma_f32_16x16x32_bf16 v[50:53], v[74:77], v[70:73], v[50:53]
	ds_read_b128 v[74:77], v82 offset:17472
	s_waitcnt lgkmcnt(0)
	v_mfma_f32_16x16x32_bf16 v[54:57], v[74:77], v[70:73], v[54:57]
	ds_read_b128 v[74:77], v82 offset:21824
	s_waitcnt lgkmcnt(0)
	v_mfma_f32_16x16x32_bf16 v[58:61], v[74:77], v[70:73], v[58:61]
	ds_read_b128 v[74:77], v82 offset:26176
	s_waitcnt lgkmcnt(0)
	v_mfma_f32_16x16x32_bf16 v[62:65], v[74:77], v[70:73], v[62:65]
	ds_read_b128 v[74:77], v82 offset:30528
	s_waitcnt lgkmcnt(0)
	v_mfma_f32_16x16x32_bf16 v[34:37], v[74:77], v[70:73], v[34:37]
	ds_read_b128 v[70:73], v78 offset:34944
	ds_read_b128 v[74:77], v82 offset:128
	s_waitcnt lgkmcnt(0)
	v_mfma_f32_16x16x32_bf16 v[38:41], v[74:77], v[70:73], v[38:41]
	ds_read_b128 v[74:77], v82 offset:4480
	s_waitcnt lgkmcnt(0)
	v_mfma_f32_16x16x32_bf16 v[42:45], v[74:77], v[70:73], v[42:45]
	ds_read_b128 v[74:77], v82 offset:8832
	s_waitcnt lgkmcnt(0)
; __device__ __forceinline__ float fexp2(float x) { return __builtin_amdgcn_exp2f(x); }
; __device__ __forceinline__ void ret_unit(LAS unsigned char* lds, const bfu* PROJ, const bfu* RT, const float* gn_g, bfu* CAT, int u) {
;     ...
;     wave_mma(acc, Ks, Vt, m0, fr, fq);
;     const float xi = fexp2(lg * (float)(c + 1)); float s = 0.f;
; #pragma unroll
;     for (int t = 0; t < 8; ++t) { acc[t] = acc[t] + cr[t] * xi; s += (acc[t][0] + acc[t][1]) + (acc[t][2] + acc[t][3]); }
;     s += __shfl_xor(s, 16); s += __shfl_xor(s, 32); const float mu = s * (1.f / 128.f); float q = 0.f;
	v_mfma_f32_16x16x32_bf16 v[46:49], v[74:77], v[70:73], v[46:49]
	ds_read_b128 v[74:77], v82 offset:13184
	s_waitcnt lgkmcnt(0)
	v_mfma_f32_16x16x32_bf16 v[50:53], v[74:77], v[70:73], v[50:53]
	ds_read_b128 v[74:77], v82 offset:17536
	s_waitcnt lgkmcnt(0)
	v_mfma_f32_16x16x32_bf16 v[54:57], v[74:77], v[70:73], v[54:57]
	ds_read_b128 v[74:77], v82 offset:21888
	s_waitcnt lgkmcnt(0)
	v_mfma_f32_16x16x32_bf16 v[58:61], v[74:77], v[70:73], v[58:61]
	ds_read_b128 v[74:77], v82 offset:26240
	s_waitcnt lgkmcnt(0)
	v_mfma_f32_16x16x32_bf16 v[62:65], v[74:77], v[70:73], v[62:65]
	ds_read_b128 v[74:77], v82 offset:30592
	s_waitcnt lgkmcnt(0)
	v_mfma_f32_16x16x32_bf16 v[34:37], v[74:77], v[70:73], v[34:37]
	ds_read_b128 v[70:73], v78 offset:35008
	ds_read_b128 v[74:77], v82 offset:192
	s_waitcnt lgkmcnt(0)
	v_mfma_f32_16x16x32_bf16 v[38:41], v[74:77], v[70:73], v[38:41]
	ds_read_b128 v[74:77], v82 offset:4544
	s_waitcnt lgkmcnt(0)
	v_mfma_f32_16x16x32_bf16 v[74:77], v[74:77], v[70:73], v[42:45]
	s_nop 2
	ds_read_b128 v[42:45], v82 offset:8896
	s_waitcnt lgkmcnt(0)
	v_mfma_f32_16x16x32_bf16 v[78:81], v[42:45], v[70:73], v[46:49]
	ds_read_b128 v[42:45], v82 offset:13248
	s_waitcnt lgkmcnt(0)
	v_mfma_f32_16x16x32_bf16 v[48:51], v[42:45], v[70:73], v[50:53]
	ds_read_b128 v[42:45], v82 offset:17600
	s_waitcnt lgkmcnt(0)
	v_mfma_f32_16x16x32_bf16 v[52:55], v[42:45], v[70:73], v[54:57]
	ds_read_b128 v[42:45], v82 offset:21952
	s_waitcnt lgkmcnt(0)
	v_mfma_f32_16x16x32_bf16 v[56:59], v[42:45], v[70:73], v[58:61]
	ds_read_b128 v[42:45], v82 offset:26304
	s_waitcnt lgkmcnt(0)
	v_mfma_f32_16x16x32_bf16 v[60:63], v[42:45], v[70:73], v[62:65]
	ds_read_b128 v[42:45], v82 offset:30656
	s_waitcnt lgkmcnt(0)
	v_mfma_f32_16x16x32_bf16 v[70:73], v[42:45], v[70:73], v[34:37]
	s_nop 2
	v_add_u32_e32 v34, 1, v66
	v_cvt_f32_i32_e32 v34, v34
	v_mul_f32_e32 v34, v67, v34
	v_exp_f32_e32 v64, v34
	v_ashrrev_i32_e32 v67, 31, v66
	v_pk_fma_f32 v[46:47], v[64:65], v[10:11], v[38:39] op_sel_hi:[0,1,1]
	v_pk_fma_f32 v[42:43], v[64:65], v[30:31], v[74:75] op_sel_hi:[0,1,1]
	v_pk_fma_f32 v[44:45], v[64:65], v[12:13], v[40:41] op_sel_hi:[0,1,1]
	v_pk_fma_f32 v[40:41], v[64:65], v[32:33], v[76:77] op_sel_hi:[0,1,1]
	v_mov_b32_e32 v10, v46
	v_mov_b32_e32 v11, v42
	v_mov_b32_e32 v12, v47
	v_mov_b32_e32 v13, v43
	v_pk_add_f32 v[10:11], v[10:11], v[12:13]
	v_mov_b32_e32 v12, v44
	v_mov_b32_e32 v13, v40
	v_mov_b32_e32 v30, v45
	v_mov_b32_e32 v31, v41
	v_pk_fma_f32 v[38:39], v[64:65], v[2:3], v[78:79] op_sel_hi:[0,1,1]
	v_pk_fma_f32 v[36:37], v[64:65], v[4:5], v[80:81] op_sel_hi:[0,1,1]
	v_pk_add_f32 v[12:13], v[12:13], v[30:31]
	v_pk_mov_b32 v[2:3], v[38:39], v[36:37] op_sel:[1,0]
	v_mov_b32_e32 v4, v38
	v_mov_b32_e32 v5, v37
	v_pk_add_f32 v[10:11], v[10:11], v[12:13]
	v_pk_add_f32 v[2:3], v[2:3], v[4:5]
	v_add_f32_e32 v10, 0, v10
	v_pk_add_f32 v[2:3], v[2:3], v[2:3] op_sel:[0,1] op_sel_hi:[1,0]
	v_pk_fma_f32 v[32:33], v[64:65], v[16:17], v[50:51] op_sel_hi:[0,1,1]
	v_pk_fma_f32 v[34:35], v[64:65], v[14:15], v[48:49] op_sel_hi:[0,1,1]
	v_pk_fma_f32 v[28:29], v[64:65], v[28:29], v[54:55] op_sel_hi:[0,1,1]
	v_pk_fma_f32 v[30:31], v[64:65], v[26:27], v[52:53] op_sel_hi:[0,1,1]
	v_add_f32_e32 v10, v10, v11
	v_add_f32_e32 v4, v34, v35
	v_add_f32_e32 v12, v32, v33
	v_mov_b32_e32 v11, v30
	v_mov_b32_e32 v3, v31
	v_mov_b32_e32 v5, v28
	v_mov_b32_e32 v13, v29
	v_pk_add_f32 v[2:3], v[10:11], v[2:3]
	v_pk_add_f32 v[4:5], v[4:5], v[12:13]
	v_pk_fma_f32 v[26:27], v[64:65], v[6:7], v[56:57] op_sel_hi:[0,1,1]
	v_pk_fma_f32 v[16:17], v[64:65], v[8:9], v[58:59] op_sel_hi:[0,1,1]
	v_pk_add_f32 v[2:3], v[2:3], v[4:5]
	v_pk_mov_b32 v[4:5], v[26:27], v[16:17] op_sel:[1,0]
	v_mov_b32_e32 v6, v26
	v_mov_b32_e32 v7, v17
	v_pk_add_f32 v[4:5], v[4:5], v[6:7]
	v_pk_add_f32 v[2:3], v[2:3], v[2:3] op_sel:[0,1] op_sel_hi:[1,0]
	v_pk_add_f32 v[4:5], v[4:5], v[4:5] op_sel:[0,1] op_sel_hi:[1,0]
	v_pk_fma_f32 v[10:11], v[64:65], v[20:21], v[62:63] op_sel_hi:[0,1,1]
	v_pk_fma_f32 v[12:13], v[64:65], v[18:19], v[60:61] op_sel_hi:[0,1,1]
	v_pk_fma_f32 v[6:7], v[64:65], v[24:25], v[72:73] op_sel_hi:[0,1,1]
	v_pk_fma_f32 v[8:9], v[64:65], v[22:23], v[70:71] op_sel_hi:[0,1,1]
	v_add_f32_e32 v14, v12, v13
	v_add_f32_e32 v18, v10, v11
	v_mov_b32_e32 v3, v8
	v_mov_b32_e32 v5, v9
	v_mov_b32_e32 v15, v6
	v_mov_b32_e32 v19, v7
	v_pk_add_f32 v[2:3], v[2:3], v[4:5]
	v_pk_add_f32 v[4:5], v[14:15], v[18:19]
	s_nop 0
	v_pk_add_f32 v[2:3], v[2:3], v[4:5]
	v_and_b32_e32 v4, 64, v240
	v_add_f32_e32 v2, v2, v3
	v_xor_b32_e32 v3, 16, v240
	v_add_u32_e32 v4, 64, v4
	v_cmp_lt_i32_e32 vcc, v3, v4
	s_nop 1
	v_cndmask_b32_e32 v3, v240, v3, vcc
	v_lshlrev_b32_e32 v20, 2, v3
	ds_bpermute_b32 v3, v20, v2
	s_waitcnt lgkmcnt(0)
	v_add_f32_e32 v2, v2, v3
	v_xor_b32_e32 v3, 32, v240
	v_cmp_lt_i32_e32 vcc, v3, v4
	s_nop 1
	v_cndmask_b32_e32 v3, v240, v3, vcc
	v_lshlrev_b32_e32 v21, 2, v3
	ds_bpermute_b32 v3, v21, v2
	s_waitcnt lgkmcnt(0)
; __device__ __forceinline__ void ret_unit(LAS unsigned char* lds, const bfu* PROJ, const bfu* RT, const float* gn_g, bfu* CAT, int u) {
;     ...
;     s += __shfl_xor(s, 16); s += __shfl_xor(s, 32); const float mu = s * (1.f / 128.f); float q = 0.f;
; #pragma unroll
;     for (int t = 0; t < 8; ++t) { acc[t] = acc[t] - mu; q += (acc[t][0] * acc[t][0] + acc[t][1] * acc[t][1]) + (acc[t][2] * acc[t][2] + acc[t][3] * acc[t][3]); }
;     q += __shfl_xor(q, 16); q += __shfl_xor(q, 32); const float rstd = 1.f / sqrtf(q * (1.f / 128.f) + EPS);
;     const bfu* gp = P0 + (size_t)c * INW + C_RG + 4 * fq; bfu* op = CAT + (row0 + c) * DM + h * 128 + 4 * fq; const float* gg = gn_g + h * 128 + 4 * fq;
; #pragma unroll
;     for (int t = 0; t < 8; ++t) { const v2u gw = *(const v2u*)(gp + 16 * t); const f32x4 g4 = *(const f32x4*)(gg + 16 * t);
	v_add_f32_e32 v22, v2, v3
	v_fmamk_f32 v47, v22, 0xbc000000, v47
	v_fmamk_f32 v43, v22, 0xbc000000, v43
	v_fmamk_f32 v45, v22, 0xbc000000, v45
	v_fmac_f32_e32 v46, 0xbc000000, v22
	v_fmamk_f32 v41, v22, 0xbc000000, v41
	v_fmac_f32_e32 v42, 0xbc000000, v22
	v_mov_b32_e32 v4, v47
	v_mov_b32_e32 v5, v43
	v_fmac_f32_e32 v44, 0xbc000000, v22
	v_fmac_f32_e32 v40, 0xbc000000, v22
	v_mov_b32_e32 v2, v46
	v_mov_b32_e32 v3, v42
	v_pk_mul_f32 v[4:5], v[4:5], v[4:5]
	v_mov_b32_e32 v14, v45
	v_mov_b32_e32 v15, v41
	v_pk_fma_f32 v[2:3], v[2:3], v[2:3], v[4:5]
	v_mov_b32_e32 v4, v44
	v_mov_b32_e32 v5, v40
	v_pk_mul_f32 v[14:15], v[14:15], v[14:15]
	v_fmamk_f32 v39, v22, 0xbc000000, v39
	v_pk_fma_f32 v[4:5], v[4:5], v[4:5], v[14:15]
	v_fmac_f32_e32 v38, 0xbc000000, v22
	v_pk_add_f32 v[2:3], v[2:3], v[4:5]
	v_fmamk_f32 v37, v22, 0xbc000000, v37
	v_fmac_f32_e32 v36, 0xbc000000, v22
	v_pk_add_f32 v[2:3], v[2:3], v[2:3] op_sel_hi:[0,1]
	v_pk_mul_f32 v[4:5], v[36:37], v[36:37]
	v_pk_mul_f32 v[14:15], v[38:39], v[38:39]
	v_fmac_f32_e32 v34, 0xbc000000, v22
	v_pk_mov_b32 v[18:19], v[14:15], v[4:5] op_sel:[1,0]
	v_mov_b32_e32 v15, v5
	v_fmac_f32_e32 v32, 0xbc000000, v22
	v_fmamk_f32 v35, v22, 0xbc000000, v35
	v_mul_f32_e32 v2, v34, v34
	v_pk_add_f32 v[4:5], v[18:19], v[14:15]
	v_fmamk_f32 v33, v22, 0xbc000000, v33
	v_pk_fma_f32 v[14:15], v[34:35], v[34:35], v[2:3] op_sel_hi:[1,1,0]
	v_mul_f32_e32 v2, v32, v32
	v_pk_add_f32 v[4:5], v[4:5], v[4:5] op_sel_hi:[0,1]
	v_pk_fma_f32 v[18:19], v[32:33], v[32:33], v[2:3] op_sel_hi:[1,1,0]
	v_fmamk_f32 v29, v22, 0xbc000000, v29
	v_fmac_f32_e32 v28, 0xbc000000, v22
	v_fmamk_f32 v31, v22, 0xbc000000, v31
	v_fmac_f32_e32 v30, 0xbc000000, v22
	v_mul_f32_e32 v14, v30, v30
	v_mul_f32_e32 v18, v31, v31
	v_mul_f32_e32 v4, v28, v28
	v_mul_f32_e32 v2, v29, v29
	v_pk_add_f32 v[14:15], v[14:15], v[18:19]
	v_pk_add_f32 v[2:3], v[4:5], v[2:3]
	v_fmamk_f32 v27, v22, 0xbc000000, v27
	v_pk_add_f32 v[2:3], v[14:15], v[2:3]
	v_fmac_f32_e32 v26, 0xbc000000, v22
	v_fmamk_f32 v17, v22, 0xbc000000, v17
	v_fmac_f32_e32 v16, 0xbc000000, v22
	v_pk_add_f32 v[2:3], v[2:3], v[2:3] op_sel_hi:[0,1]
	v_pk_mul_f32 v[4:5], v[16:17], v[16:17]
	v_pk_mul_f32 v[14:15], v[26:27], v[26:27]
	v_fmac_f32_e32 v12, 0xbc000000, v22
	v_pk_mov_b32 v[18:19], v[14:15], v[4:5] op_sel:[1,0]
	v_mov_b32_e32 v15, v5
	v_fmac_f32_e32 v10, 0xbc000000, v22
	v_fmamk_f32 v13, v22, 0xbc000000, v13
	v_mul_f32_e32 v2, v12, v12
	v_pk_add_f32 v[4:5], v[18:19], v[14:15]
	v_fmamk_f32 v11, v22, 0xbc000000, v11
	v_pk_fma_f32 v[14:15], v[12:13], v[12:13], v[2:3] op_sel_hi:[1,1,0]
	v_mul_f32_e32 v2, v10, v10
	v_pk_add_f32 v[4:5], v[4:5], v[4:5] op_sel_hi:[0,1]
	v_pk_fma_f32 v[18:19], v[10:11], v[10:11], v[2:3] op_sel_hi:[1,1,0]
	v_fmamk_f32 v7, v22, 0xbc000000, v7
	v_fmac_f32_e32 v6, 0xbc000000, v22
	v_fmamk_f32 v9, v22, 0xbc000000, v9
	v_fmac_f32_e32 v8, 0xbc000000, v22
	v_mul_f32_e32 v14, v8, v8
	v_mul_f32_e32 v18, v9, v9
	v_mul_f32_e32 v4, v6, v6
	v_mul_f32_e32 v2, v7, v7
	v_pk_add_f32 v[14:15], v[14:15], v[18:19]
	v_pk_add_f32 v[2:3], v[4:5], v[2:3]
	s_nop 0
	v_pk_add_f32 v[2:3], v[14:15], v[2:3]
	s_nop 0
	v_add_f32_e32 v2, v2, v3
	ds_bpermute_b32 v3, v20, v2
	s_waitcnt lgkmcnt(0)
	v_add_f32_e32 v2, v2, v3
	ds_bpermute_b32 v3, v21, v2
	s_waitcnt lgkmcnt(0)
	v_add_f32_e32 v2, v2, v3
	v_fmamk_f32 v2, v2, 0x3c000000, v236
	v_cmp_gt_f32_e32 vcc, s68, v2
	v_mul_f32_e32 v3, 0x4f800000, v2
	s_nop 0
	v_cndmask_b32_e32 v2, v2, v3, vcc
	v_sqrt_f32_e32 v3, v2
	s_nop 0
	v_add_u32_e32 v4, -1, v3
	v_fma_f32 v5, -v4, v3, v2
	v_cmp_ge_f32_e64 s[40:41], 0, v5
	v_add_u32_e32 v5, 1, v3
	s_nop 0
	v_cndmask_b32_e64 v4, v3, v4, s[40:41]
	v_fma_f32 v3, -v5, v3, v2
	v_cmp_lt_f32_e64 s[40:41], 0, v3
	s_nop 1
	v_cndmask_b32_e64 v3, v4, v5, s[40:41]
	v_mul_f32_e32 v4, 0x37800000, v3
	v_cndmask_b32_e32 v3, v3, v4, vcc
	v_cmp_class_f32_e32 vcc, v2, v234
	s_nop 1
	v_cndmask_b32_e32 v2, v3, v2, vcc
	v_div_scale_f32 v3, s[22:23], v2, v2, 1.0
	v_rcp_f32_e32 v4, v3
	s_nop 0
	v_fma_f32 v5, -v3, v4, 1.0
	v_fmac_f32_e32 v4, v5, v4
	v_div_scale_f32 v5, vcc, 1.0, v2, 1.0
	v_mul_f32_e32 v14, v5, v4
	v_fma_f32 v15, -v3, v14, v5
	v_fmac_f32_e32 v14, v15, v4
	v_fma_f32 v3, -v3, v14, v5
	v_div_fmas_f32 v3, v3, v4, v14
	v_lshl_add_u64 v[4:5], s[46:47], 0, v[66:67]
	v_div_fixup_f32 v14, v3, v2, 1.0
	v_mov_b64_e32 v[2:3], s[56:57]
	v_lshlrev_b64 v[4:5], 12, v[4:5]
	v_mad_i64_i32 v[2:3], s[22:23], v66, s61, v[2:3]
	v_lshl_add_u64 v[4:5], s[44:45], 0, v[4:5]
	v_lshl_add_u64 v[2:3], v[2:3], 0, v[0:1]
	s_mov_b64 s[22:23], 0x1200
	v_lshl_add_u64 v[4:5], v[4:5], 0, s[52:53]
	v_lshl_add_u64 v[20:21], v[2:3], 0, s[22:23]
	v_lshl_add_u64 v[22:23], v[4:5], 0, v[0:1]
	s_mov_b64 s[22:23], 0x29600000
	v_lshl_add_u64 v[18:19], v[22:23], 0, s[22:23]
	s_lshl_b64 s[22:23], s[50:51], 2
	v_add_co_u32_e32 v2, vcc, s62, v2
	s_add_u32 s40, s20, s22
	s_nop 0
	v_addc_co_u32_e32 v3, vcc, 0, v3, vcc
	s_addc_u32 s41, s35, s23
	global_load_dwordx2 v[120:121], v[2:3], off offset:512
	global_load_dwordx4 v[122:125], v69, s[40:41]
	global_load_dwordx2 v[126:127], v[20:21], off offset:32
	global_load_dwordx4 v[128:131], v69, s[40:41] offset:64
	global_load_dwordx2 v[132:133], v[20:21], off offset:64
	global_load_dwordx4 v[134:137], v69, s[40:41] offset:128
	global_load_dwordx2 v[138:139], v[20:21], off offset:96
	global_load_dwordx4 v[140:143], v69, s[40:41] offset:192
	global_load_dwordx2 v[144:145], v[20:21], off offset:128
	global_load_dwordx4 v[146:149], v69, s[40:41] offset:256
	global_load_dwordx2 v[150:151], v[20:21], off offset:160
	global_load_dwordx4 v[152:155], v69, s[40:41] offset:320
	global_load_dwordx2 v[156:157], v[20:21], off offset:192
	global_load_dwordx4 v[158:161], v69, s[40:41] offset:384
	global_load_dwordx2 v[162:163], v[20:21], off offset:224
	global_load_dwordx4 v[164:167], v69, s[40:41] offset:448
	s_nop 0
	s_mov_b32 s20, 0x29600000
	s_waitcnt vmcnt(0)
; __device__ __forceinline__ unsigned pk2(float lo, float hi) { return pg8::cvt_pk_bf16(lo, hi); }
; __device__ __forceinline__ float silu_f(float g) { return g * frcp(1.f + fexp2(-LOG2E * g)); }
; __device__ __forceinline__ void ret_unit(LAS unsigned char* lds, const bfu* PROJ, const bfu* RT, const float* gn_g, bfu* CAT, int u) {
;     ...
;     for (int t = 0; t < 8; ++t) { const v2u gw = *(const v2u*)(gp + 16 * t); const f32x4 g4 = *(const f32x4*)(gg + 16 * t);
;         const float o0 = silu_f(bflo(gw.x)) * acc[t][0] * rstd * g4.x, o1 = silu_f(bfhi(gw.x)) * acc[t][1] * rstd * g4.y, o2 = silu_f(bflo(gw.y)) * acc[t][2] * rstd * g4.z, o3 = silu_f(bfhi(gw.y)) * acc[t][3] * rstd * g4.w;
;         v2u w; w.x = pk2(o0, o1); w.y = pk2(o2, o3); *(v2u*)(op + 16 * t) = w; }
	v_lshlrev_b32_e32 v48, 16, v120
	v_mul_f32_e32 v0, 0xbfb8aa3b, v48
	v_exp_f32_e32 v0, v0
	v_and_b32_e32 v49, 0xffff0000, v120
	v_lshlrev_b32_e32 v24, 16, v121
	v_and_b32_e32 v25, 0xffff0000, v121
	v_add_f32_e32 v0, 1.0, v0
	v_rcp_f32_e32 v50, v0
	v_mul_f32_e32 v0, 0xbfb8aa3b, v49
	v_exp_f32_e32 v0, v0
	s_nop 0
	v_add_f32_e32 v0, 1.0, v0
	v_rcp_f32_e32 v51, v0
	v_mul_f32_e32 v0, 0xbfb8aa3b, v24
	v_exp_f32_e32 v0, v0
	v_pk_mul_f32 v[48:49], v[50:51], v[48:49]
	s_nop 0
	v_pk_mul_f32 v[46:47], v[46:47], v[48:49]
	v_add_f32_e32 v0, 1.0, v0
	v_pk_mul_f32 v[46:47], v[46:47], v[14:15] op_sel_hi:[1,0]
	v_pk_mul_f32 v[2:3], v[122:123], v[46:47]
	v_rcp_f32_e32 v46, v0
	v_mul_f32_e32 v0, 0xbfb8aa3b, v25
	v_exp_f32_e32 v0, v0
	v_cvt_pk_bf16_f32 v2, v2, v3
	v_add_f32_e32 v0, 1.0, v0
	v_rcp_f32_e32 v47, v0
	s_nop 0
	v_pk_mul_f32 v[24:25], v[46:47], v[24:25]
	s_nop 0
	v_pk_mul_f32 v[24:25], v[44:45], v[24:25]
	s_nop 0
	v_pk_mul_f32 v[24:25], v[24:25], v[14:15] op_sel_hi:[1,0]
	s_nop 0
	v_pk_mul_f32 v[4:5], v[124:125], v[24:25]
	s_nop 0
	v_cvt_pk_bf16_f32 v3, v4, v5
	v_add_co_u32_e32 v4, vcc, s20, v22
	s_nop 1
	v_addc_co_u32_e32 v5, vcc, 0, v23, vcc
	global_store_dwordx2 v[4:5], v[2:3], off
	s_nop 0
	v_lshlrev_b32_e32 v24, 16, v126
	v_mul_f32_e32 v0, 0xbfb8aa3b, v24
	v_exp_f32_e32 v0, v0
	v_and_b32_e32 v25, 0xffff0000, v126
	v_lshlrev_b32_e32 v22, 16, v127
	v_and_b32_e32 v23, 0xffff0000, v127
	v_add_f32_e32 v0, 1.0, v0
	v_rcp_f32_e32 v44, v0
	v_mul_f32_e32 v0, 0xbfb8aa3b, v25
	v_exp_f32_e32 v0, v0
	s_nop 0
	v_add_f32_e32 v0, 1.0, v0
	v_rcp_f32_e32 v45, v0
	v_mul_f32_e32 v0, 0xbfb8aa3b, v22
	v_exp_f32_e32 v0, v0
	v_pk_mul_f32 v[24:25], v[44:45], v[24:25]
	s_nop 0
	v_pk_mul_f32 v[24:25], v[42:43], v[24:25]
	v_add_f32_e32 v0, 1.0, v0
	v_pk_mul_f32 v[24:25], v[24:25], v[14:15] op_sel_hi:[1,0]
	v_pk_mul_f32 v[2:3], v[128:129], v[24:25]
	v_rcp_f32_e32 v24, v0
	v_mul_f32_e32 v0, 0xbfb8aa3b, v23
	v_exp_f32_e32 v0, v0
	v_cvt_pk_bf16_f32 v2, v2, v3
	v_add_f32_e32 v0, 1.0, v0
	v_rcp_f32_e32 v25, v0
	s_nop 0
	v_pk_mul_f32 v[22:23], v[24:25], v[22:23]
	s_nop 0
	v_pk_mul_f32 v[22:23], v[40:41], v[22:23]
	s_nop 0
	v_pk_mul_f32 v[22:23], v[22:23], v[14:15] op_sel_hi:[1,0]
	s_nop 0
	v_pk_mul_f32 v[4:5], v[130:131], v[22:23]
	s_nop 0
	v_cvt_pk_bf16_f32 v3, v4, v5
	global_store_dwordx2 v[18:19], v[2:3], off offset:32
	s_nop 0
	v_lshlrev_b32_e32 v24, 16, v132
	v_mul_f32_e32 v0, 0xbfb8aa3b, v24
	v_exp_f32_e32 v0, v0
	v_and_b32_e32 v25, 0xffff0000, v132
	v_lshlrev_b32_e32 v22, 16, v133
	v_and_b32_e32 v23, 0xffff0000, v133
	v_add_f32_e32 v0, 1.0, v0
	v_rcp_f32_e32 v40, v0
	v_mul_f32_e32 v0, 0xbfb8aa3b, v25
	v_exp_f32_e32 v0, v0
	s_nop 0
	v_add_f32_e32 v0, 1.0, v0
	v_rcp_f32_e32 v41, v0
	v_mul_f32_e32 v0, 0xbfb8aa3b, v22
	v_exp_f32_e32 v0, v0
	v_pk_mul_f32 v[24:25], v[40:41], v[24:25]
	s_nop 0
	v_pk_mul_f32 v[24:25], v[38:39], v[24:25]
	v_add_f32_e32 v0, 1.0, v0
	v_pk_mul_f32 v[24:25], v[24:25], v[14:15] op_sel_hi:[1,0]
	v_pk_mul_f32 v[2:3], v[134:135], v[24:25]
	v_rcp_f32_e32 v24, v0
	v_mul_f32_e32 v0, 0xbfb8aa3b, v23
	v_exp_f32_e32 v0, v0
	v_cvt_pk_bf16_f32 v2, v2, v3
	v_add_f32_e32 v0, 1.0, v0
	v_rcp_f32_e32 v25, v0
	s_nop 0
	v_pk_mul_f32 v[22:23], v[24:25], v[22:23]
	s_nop 0
	v_pk_mul_f32 v[22:23], v[36:37], v[22:23]
	s_nop 0
	v_pk_mul_f32 v[22:23], v[22:23], v[14:15] op_sel_hi:[1,0]
	s_nop 0
	v_pk_mul_f32 v[4:5], v[136:137], v[22:23]
	s_nop 0
	v_cvt_pk_bf16_f32 v3, v4, v5
	global_store_dwordx2 v[18:19], v[2:3], off offset:64
	s_nop 0
	v_lshlrev_b32_e32 v24, 16, v138
	v_mul_f32_e32 v0, 0xbfb8aa3b, v24
	v_exp_f32_e32 v0, v0
	v_and_b32_e32 v25, 0xffff0000, v138
	v_lshlrev_b32_e32 v22, 16, v139
	v_and_b32_e32 v23, 0xffff0000, v139
	v_add_f32_e32 v0, 1.0, v0
	v_rcp_f32_e32 v36, v0
	v_mul_f32_e32 v0, 0xbfb8aa3b, v25
	v_exp_f32_e32 v0, v0
	s_nop 0
	v_add_f32_e32 v0, 1.0, v0
	v_rcp_f32_e32 v37, v0
	v_mul_f32_e32 v0, 0xbfb8aa3b, v22
	v_exp_f32_e32 v0, v0
	v_pk_mul_f32 v[24:25], v[36:37], v[24:25]
	s_nop 0
	v_pk_mul_f32 v[24:25], v[34:35], v[24:25]
	v_add_f32_e32 v0, 1.0, v0
	v_pk_mul_f32 v[24:25], v[24:25], v[14:15] op_sel_hi:[1,0]
	v_pk_mul_f32 v[2:3], v[140:141], v[24:25]
	v_rcp_f32_e32 v24, v0
	v_mul_f32_e32 v0, 0xbfb8aa3b, v23
	v_exp_f32_e32 v0, v0
	v_cvt_pk_bf16_f32 v2, v2, v3
	v_add_f32_e32 v0, 1.0, v0
	v_rcp_f32_e32 v25, v0
	s_nop 0
	v_pk_mul_f32 v[22:23], v[24:25], v[22:23]
	s_nop 0
	v_pk_mul_f32 v[22:23], v[32:33], v[22:23]
	s_nop 0
	v_pk_mul_f32 v[22:23], v[22:23], v[14:15] op_sel_hi:[1,0]
	s_nop 0
	v_pk_mul_f32 v[4:5], v[142:143], v[22:23]
	s_nop 0
	v_cvt_pk_bf16_f32 v3, v4, v5
	global_store_dwordx2 v[18:19], v[2:3], off offset:96
; __device__ __forceinline__ unsigned pk2(float lo, float hi) { return pg8::cvt_pk_bf16(lo, hi); }
; __device__ __forceinline__ float silu_f(float g) { return g * frcp(1.f + fexp2(-LOG2E * g)); }
; __device__ __forceinline__ void ret_unit(LAS unsigned char* lds, const bfu* PROJ, const bfu* RT, const float* gn_g, bfu* CAT, int u) {
;     ...
;     for (int t = 0; t < 8; ++t) { const v2u gw = *(const v2u*)(gp + 16 * t); const f32x4 g4 = *(const f32x4*)(gg + 16 * t);
;         const float o0 = silu_f(bflo(gw.x)) * acc[t][0] * rstd * g4.x, o1 = silu_f(bfhi(gw.x)) * acc[t][1] * rstd * g4.y, o2 = silu_f(bflo(gw.y)) * acc[t][2] * rstd * g4.z, o3 = silu_f(bfhi(gw.y)) * acc[t][3] * rstd * g4.w;
;         v2u w; w.x = pk2(o0, o1); w.y = pk2(o2, o3); *(v2u*)(op + 16 * t) = w; }
;     __syncthreads();
	s_nop 0
	v_lshlrev_b32_e32 v24, 16, v144
	v_mul_f32_e32 v0, 0xbfb8aa3b, v24
	v_exp_f32_e32 v0, v0
	v_and_b32_e32 v25, 0xffff0000, v144
	v_lshlrev_b32_e32 v22, 16, v145
	v_and_b32_e32 v23, 0xffff0000, v145
	v_add_f32_e32 v0, 1.0, v0
	v_rcp_f32_e32 v32, v0
	v_mul_f32_e32 v0, 0xbfb8aa3b, v25
	v_exp_f32_e32 v0, v0
	s_nop 0
	v_add_f32_e32 v0, 1.0, v0
	v_rcp_f32_e32 v33, v0
	v_mul_f32_e32 v0, 0xbfb8aa3b, v22
	v_exp_f32_e32 v0, v0
	v_pk_mul_f32 v[24:25], v[32:33], v[24:25]
	s_nop 0
	v_pk_mul_f32 v[24:25], v[30:31], v[24:25]
	v_add_f32_e32 v0, 1.0, v0
	v_pk_mul_f32 v[24:25], v[24:25], v[14:15] op_sel_hi:[1,0]
	v_pk_mul_f32 v[2:3], v[146:147], v[24:25]
	v_rcp_f32_e32 v24, v0
	v_mul_f32_e32 v0, 0xbfb8aa3b, v23
	v_exp_f32_e32 v0, v0
	v_cvt_pk_bf16_f32 v2, v2, v3
	v_add_f32_e32 v0, 1.0, v0
	v_rcp_f32_e32 v25, v0
	s_nop 0
	v_pk_mul_f32 v[22:23], v[24:25], v[22:23]
	s_nop 0
	v_pk_mul_f32 v[22:23], v[28:29], v[22:23]
	s_nop 0
	v_pk_mul_f32 v[22:23], v[22:23], v[14:15] op_sel_hi:[1,0]
	s_nop 0
	v_pk_mul_f32 v[4:5], v[148:149], v[22:23]
	s_nop 0
	v_cvt_pk_bf16_f32 v3, v4, v5
	global_store_dwordx2 v[18:19], v[2:3], off offset:128
	s_nop 0
	v_lshlrev_b32_e32 v24, 16, v150
	v_mul_f32_e32 v0, 0xbfb8aa3b, v24
	v_exp_f32_e32 v0, v0
	v_and_b32_e32 v25, 0xffff0000, v150
	v_lshlrev_b32_e32 v22, 16, v151
	v_and_b32_e32 v23, 0xffff0000, v151
	v_add_f32_e32 v0, 1.0, v0
	v_rcp_f32_e32 v28, v0
	v_mul_f32_e32 v0, 0xbfb8aa3b, v25
	v_exp_f32_e32 v0, v0
	s_nop 0
	v_add_f32_e32 v0, 1.0, v0
	v_rcp_f32_e32 v29, v0
	v_mul_f32_e32 v0, 0xbfb8aa3b, v22
	v_exp_f32_e32 v0, v0
	v_pk_mul_f32 v[24:25], v[28:29], v[24:25]
	s_nop 0
	v_pk_mul_f32 v[24:25], v[26:27], v[24:25]
	v_add_f32_e32 v0, 1.0, v0
	v_pk_mul_f32 v[24:25], v[14:15], v[24:25] op_sel_hi:[0,1]
	v_pk_mul_f32 v[2:3], v[152:153], v[24:25]
	v_rcp_f32_e32 v24, v0
	v_mul_f32_e32 v0, 0xbfb8aa3b, v23
	v_exp_f32_e32 v0, v0
	v_cvt_pk_bf16_f32 v2, v2, v3
	v_add_f32_e32 v0, 1.0, v0
	v_rcp_f32_e32 v25, v0
	s_nop 0
	v_pk_mul_f32 v[22:23], v[24:25], v[22:23]
	s_nop 0
	v_pk_mul_f32 v[16:17], v[16:17], v[22:23]
	s_nop 0
	v_pk_mul_f32 v[16:17], v[14:15], v[16:17] op_sel_hi:[0,1]
	v_pk_mul_f32 v[4:5], v[154:155], v[16:17]
	s_nop 0
	v_cvt_pk_bf16_f32 v3, v4, v5
	global_store_dwordx2 v[18:19], v[2:3], off offset:160
	s_nop 0
	v_lshlrev_b32_e32 v22, 16, v156
	v_mul_f32_e32 v0, 0xbfb8aa3b, v22
	v_exp_f32_e32 v0, v0
	v_and_b32_e32 v23, 0xffff0000, v156
	v_add_f32_e32 v0, 1.0, v0
	v_rcp_f32_e32 v24, v0
	v_mul_f32_e32 v0, 0xbfb8aa3b, v23
	v_exp_f32_e32 v0, v0
	s_nop 0
	v_add_f32_e32 v0, 1.0, v0
	v_rcp_f32_e32 v25, v0
	s_nop 0
	v_pk_mul_f32 v[22:23], v[24:25], v[22:23]
	s_nop 0
	v_pk_mul_f32 v[12:13], v[12:13], v[22:23]
	s_nop 0
	v_pk_mul_f32 v[12:13], v[14:15], v[12:13] op_sel_hi:[0,1]
	v_pk_mul_f32 v[2:3], v[158:159], v[12:13]
	v_lshlrev_b32_e32 v12, 16, v157
	v_mul_f32_e32 v0, 0xbfb8aa3b, v12
	v_exp_f32_e32 v0, v0
	v_and_b32_e32 v13, 0xffff0000, v157
	v_cvt_pk_bf16_f32 v2, v2, v3
	v_add_f32_e32 v0, 1.0, v0
	v_rcp_f32_e32 v16, v0
	v_mul_f32_e32 v0, 0xbfb8aa3b, v13
	v_exp_f32_e32 v0, v0
	s_nop 0
	v_add_f32_e32 v0, 1.0, v0
	v_rcp_f32_e32 v17, v0
	s_nop 0
	v_pk_mul_f32 v[12:13], v[16:17], v[12:13]
	s_nop 0
	v_pk_mul_f32 v[10:11], v[10:11], v[12:13]
	s_nop 0
	v_pk_mul_f32 v[10:11], v[14:15], v[10:11] op_sel_hi:[0,1]
	v_pk_mul_f32 v[4:5], v[160:161], v[10:11]
	s_nop 0
	v_cvt_pk_bf16_f32 v3, v4, v5
	global_store_dwordx2 v[18:19], v[2:3], off offset:192
	s_nop 0
	v_lshlrev_b32_e32 v12, 16, v162
	v_mul_f32_e32 v0, 0xbfb8aa3b, v12
	v_exp_f32_e32 v0, v0
	v_and_b32_e32 v13, 0xffff0000, v162
	v_add_f32_e32 v0, 1.0, v0
	v_rcp_f32_e32 v16, v0
	v_mul_f32_e32 v0, 0xbfb8aa3b, v13
	v_exp_f32_e32 v0, v0
	s_nop 0
	v_add_f32_e32 v0, 1.0, v0
	v_rcp_f32_e32 v17, v0
	s_nop 0
	v_pk_mul_f32 v[12:13], v[16:17], v[12:13]
	s_nop 0
	v_pk_mul_f32 v[8:9], v[8:9], v[12:13]
	s_nop 0
	v_pk_mul_f32 v[8:9], v[14:15], v[8:9] op_sel_hi:[0,1]
	v_pk_mul_f32 v[2:3], v[164:165], v[8:9]
	v_lshlrev_b32_e32 v8, 16, v163
	v_mul_f32_e32 v0, 0xbfb8aa3b, v8
	v_exp_f32_e32 v0, v0
	v_and_b32_e32 v9, 0xffff0000, v163
	v_cvt_pk_bf16_f32 v2, v2, v3
	v_add_f32_e32 v0, 1.0, v0
	v_rcp_f32_e32 v10, v0
	v_mul_f32_e32 v0, 0xbfb8aa3b, v9
	v_exp_f32_e32 v0, v0
	s_nop 0
	v_add_f32_e32 v0, 1.0, v0
	v_rcp_f32_e32 v11, v0
	s_nop 0
	v_pk_mul_f32 v[8:9], v[10:11], v[8:9]
	s_nop 0
	v_pk_mul_f32 v[6:7], v[6:7], v[8:9]
	s_nop 0
	v_pk_mul_f32 v[6:7], v[14:15], v[6:7] op_sel_hi:[0,1]
	v_pk_mul_f32 v[4:5], v[166:167], v[6:7]
	s_nop 0
	v_cvt_pk_bf16_f32 v3, v4, v5
	global_store_dwordx2 v[18:19], v[2:3], off offset:224
	s_barrier
